# K-loop scalar address math: constants parked in scalars folded into their consuming s_add (instruction selection, 15 fewer scalar instructions per 4 loops)
# baseline (speedup 1.0000x reference)
; #define PG8_STAGEA(bufoff, gbase, voff) PG8_STAGE_X(bufoff, gbase, voff, AUXA)
; #define PG8_STAGEB(bufoff, gbase, voff) PG8_STAGE_X(bufoff, gbase, voff, AUXB)
; #define PG8_LDA(dst, b, h) do { _Pragma("unroll") for (int m = 0; m < 4; ++m) _Pragma("unroll") for (int k = 0; k < 2; ++k) dst[m][k] = *(const PG8_LAS bf16x8*)(lds + PG8_SA(b, h) + aoff + m * 2048 + k * 1024); } while (0)
; #define PG8_WAIT_V(n) asm volatile("s_waitcnt vmcnt(" #n ")" ::: "memory")
; #define PG8_WAIT_L(n) asm volatile("s_waitcnt lgkmcnt(" #n ")" ::: "memory")
;     ...
;         for (int t = t0; t < nt; t += 2) {
;             const bool last = (t == nt - 2);
;             const char* a1 = cA + (size_t)(t + 1) * kstepA;
;             const char* a2 = last ? nA : cA + (size_t)(t + 2) * kstepA; const char* b2 = last ? nB : cB + (size_t)(t + 2) * kstepB;
;             const char* a3 = a2 + kstepA; const char* b3 = b2 + kstepB;
;             if (last && has_next) S.a_ready(nxt);
;             if constexpr (SP2) {
;             PG8_LDB(B0, 0, 0); PG8_LDB(B1, 0, 1); PG8_SCHED; PG8_LDA(At, 0, 0); PG8_STAGEA(PG8_SA(1, 1), a1 + hstepA, voffA);
;     ...
;             const int relax = __builtin_amdgcn_readfirstlane((t == 0 && ui > 0) ? 1 : 0);
;             PG8_WAIT_VR(8, 24, relax); PG8_WAIT_L(0); PG8_BAR; PG8_MMA(0, 0, At, B0); PG8_MMA(0, 1, At, B1); PG8_BAR; PG8_SCHED;
;     ...
;             PG8_WAIT_V(8); PG8_WAIT_L(0); PG8_BAR; PG8_MMA(0, 0, At, B0); PG8_MMA(0, 1, At, B1); PG8_BAR; PG8_SCHED;
;     ...
;             PG8_LDA(At, 0, 1); PG8_STAGEB(PG8_SB(0, 0), b2, voffB); PG8_STAGEB(PG8_SB(0, 1), b2 + hstepB, voffB); PG8_STAGEA(PG8_SA(0, 0), a2, voffA);
;     ...
;             PG8_WAIT_VR(8, 24, relax); PG8_WAIT_L(0); PG8_BAR; PG8_MMA(1, 0, At, B0); PG8_MMA(1, 1, At, B1); PG8_BAR; PG8_SCHED;
;     ...
;             PG8_WAIT_V(8); PG8_WAIT_L(0); PG8_BAR; PG8_MMA(1, 0, At, B0); PG8_MMA(1, 1, At, B1); PG8_BAR; PG8_SCHED;
;     ...
;             PG8_LDB(B0, 1, 0); PG8_LDB(B1, 1, 1); PG8_SCHED; PG8_LDA(At, 1, 0); PG8_STAGEA(PG8_SA(0, 1), a2 + hstepA, voffA);
;             PG8_WAIT_V(8); PG8_WAIT_L(0); PG8_BAR; PG8_MMA(0, 0, At, B0); PG8_MMA(0, 1, At, B1); PG8_BAR; PG8_SCHED;
;             PG8_LDA(At, 1, 1); PG8_STAGEB(PG8_SB(1, 0), b3, voffB); PG8_STAGEB(PG8_SB(1, 1), b3 + hstepB, voffB); PG8_STAGEA(PG8_SA(1, 0), a3, voffA);
;             PG8_WAIT_V(8); PG8_WAIT_L(0); PG8_BAR; PG8_MMA(1, 0, At, B0); PG8_MMA(1, 1, At, B1); PG8_BAR; PG8_SCHED;
.LBB0_129:
	s_add_u32 s10, s8, 0xfff00080
	s_addc_u32 s11, s9, -1
	s_cmp_eq_u32 s27, 60
	s_cselect_b32 s15, s4, s11
	s_cselect_b32 s14, s5, s10
	s_cselect_b32 s11, s16, s1
	s_cselect_b32 s10, s17, s0
	s_waitcnt lgkmcnt(0)
	ds_read_b128 v[130:133], v226
	ds_read_b128 v[134:137], v226 offset:1024
	ds_read_b128 v[152:155], v226 offset:2048
	ds_read_b128 v[156:159], v226 offset:3072
	ds_read_b128 v[160:163], v226 offset:16384
	ds_read_b128 v[174:177], v226 offset:17408
	ds_read_b128 v[178:181], v226 offset:18432
	ds_read_b128 v[182:185], v226 offset:19456
	s_add_i32 m0, s51, 0xc000
	ds_read_b128 v[186:189], v172
	ds_read_b128 v[190:193], v172 offset:1024
	ds_read_b128 v[194:197], v172 offset:2048
	ds_read_b128 v[198:201], v172 offset:3072
	ds_read_b128 v[202:205], v172 offset:4096
	ds_read_b128 v[206:209], v172 offset:5120
	ds_read_b128 v[210:213], v172 offset:6144
	global_load_lds_dwordx4 v148, s[8:9]
	s_add_i32 m0, s51, 0xe000
	ds_read_b128 v[214:217], v172 offset:7168
	global_load_lds_dwordx4 v150, s[8:9]
	s_waitcnt vmcnt(8) lgkmcnt(0)
	s_nop 0
	s_nop 0
	s_nop 0
	s_barrier
	v_mfma_f32_16x16x32_bf16 v[126:129], v[130:133], v[186:189], v[126:129]
	v_mfma_f32_16x16x32_bf16 v[122:125], v[152:155], v[186:189], v[122:125]
	v_mfma_f32_16x16x32_bf16 v[110:113], v[130:133], v[194:197], v[110:113]
	v_mfma_f32_16x16x32_bf16 v[106:109], v[152:155], v[194:197], v[106:109]
	v_mfma_f32_16x16x32_bf16 v[94:97], v[130:133], v[202:205], v[94:97]
	v_mfma_f32_16x16x32_bf16 v[90:93], v[152:155], v[202:205], v[90:93]
	v_mfma_f32_16x16x32_bf16 v[78:81], v[130:133], v[210:213], v[78:81]
	v_mfma_f32_16x16x32_bf16 v[74:77], v[152:155], v[210:213], v[74:77]
	v_mfma_f32_16x16x32_bf16 v[126:129], v[134:137], v[190:193], v[126:129]
	v_mfma_f32_16x16x32_bf16 v[122:125], v[156:159], v[190:193], v[122:125]
	v_mfma_f32_16x16x32_bf16 v[110:113], v[134:137], v[198:201], v[110:113]
	v_mfma_f32_16x16x32_bf16 v[106:109], v[156:159], v[198:201], v[106:109]
	v_mfma_f32_16x16x32_bf16 v[94:97], v[134:137], v[206:209], v[94:97]
	v_mfma_f32_16x16x32_bf16 v[90:93], v[156:159], v[206:209], v[90:93]
	v_mfma_f32_16x16x32_bf16 v[78:81], v[134:137], v[214:217], v[78:81]
	v_mfma_f32_16x16x32_bf16 v[74:77], v[156:159], v[214:217], v[74:77]
	v_mfma_f32_16x16x32_bf16 v[118:121], v[160:163], v[186:189], v[118:121]
	v_mfma_f32_16x16x32_bf16 v[114:117], v[178:181], v[186:189], v[114:117]
	v_mfma_f32_16x16x32_bf16 v[102:105], v[160:163], v[194:197], v[102:105]
	v_mfma_f32_16x16x32_bf16 v[98:101], v[178:181], v[194:197], v[98:101]
	v_mfma_f32_16x16x32_bf16 v[86:89], v[160:163], v[202:205], v[86:89]
	v_mfma_f32_16x16x32_bf16 v[82:85], v[178:181], v[202:205], v[82:85]
	v_mfma_f32_16x16x32_bf16 v[70:73], v[160:163], v[210:213], v[70:73]
	v_mfma_f32_16x16x32_bf16 v[66:69], v[178:181], v[210:213], v[66:69]
	v_mfma_f32_16x16x32_bf16 v[118:121], v[174:177], v[190:193], v[118:121]
	v_mfma_f32_16x16x32_bf16 v[114:117], v[182:185], v[190:193], v[114:117]
	v_mfma_f32_16x16x32_bf16 v[102:105], v[174:177], v[198:201], v[102:105]
	v_mfma_f32_16x16x32_bf16 v[98:101], v[182:185], v[198:201], v[98:101]
	v_mfma_f32_16x16x32_bf16 v[86:89], v[174:177], v[206:209], v[86:89]
	v_mfma_f32_16x16x32_bf16 v[82:85], v[182:185], v[206:209], v[82:85]
	v_mfma_f32_16x16x32_bf16 v[70:73], v[174:177], v[214:217], v[70:73]
	v_mfma_f32_16x16x32_bf16 v[66:69], v[182:185], v[214:217], v[66:69]
	s_barrier
	s_add_i32 s18, s42, 0x10000
	s_mov_b32 m0, s18
	ds_read_b128 v[186:189], v172 offset:16384
	ds_read_b128 v[190:193], v172 offset:17408
	ds_read_b128 v[194:197], v172 offset:18432
	ds_read_b128 v[198:201], v172 offset:19456
	s_add_u32 s100, s14, 0x80
	s_addc_u32 s101, s15, 0
	global_load_lds_dwordx4 v142, s[10:11]
	s_add_i32 m0, s18, 0x2000
	s_add_u32 s18, s10, 0x100000
	s_addc_u32 s19, s11, 0
	s_add_i32 s20, s42, 0x14000
	global_load_lds_dwordx4 v138, s[10:11]
	s_mov_b32 m0, s20
	ds_read_b128 v[214:217], v172 offset:23552
	global_load_lds_dwordx4 v142, s[18:19]
	s_add_i32 m0, s20, 0x2000
	ds_read_b128 v[210:213], v172 offset:22528
	global_load_lds_dwordx4 v138, s[18:19]
	s_mov_b32 m0, s51
	ds_read_b128 v[206:209], v172 offset:21504
	global_load_lds_dwordx4 v144, s[14:15]
	s_mov_b32 m0, s68
	ds_read_b128 v[202:205], v172 offset:20480
	global_load_lds_dwordx4 v140, s[14:15]
	s_waitcnt vmcnt(8) lgkmcnt(0)
	s_nop 0
	s_barrier
	v_mfma_f32_16x16x32_bf16 v[62:65], v[130:133], v[186:189], v[62:65]
	v_mfma_f32_16x16x32_bf16 v[58:61], v[152:155], v[186:189], v[58:61]
	v_mfma_f32_16x16x32_bf16 v[46:49], v[130:133], v[194:197], v[46:49]
	v_mfma_f32_16x16x32_bf16 v[42:45], v[152:155], v[194:197], v[42:45]
	v_mfma_f32_16x16x32_bf16 v[30:33], v[130:133], v[202:205], v[30:33]
	v_mfma_f32_16x16x32_bf16 v[26:29], v[152:155], v[202:205], v[26:29]
	v_mfma_f32_16x16x32_bf16 v[12:15], v[130:133], v[210:213], v[12:15]
	v_mfma_f32_16x16x32_bf16 v[8:11], v[152:155], v[210:213], v[8:11]
	v_mfma_f32_16x16x32_bf16 v[62:65], v[134:137], v[190:193], v[62:65]
	v_mfma_f32_16x16x32_bf16 v[58:61], v[156:159], v[190:193], v[58:61]
	v_mfma_f32_16x16x32_bf16 v[46:49], v[134:137], v[198:201], v[46:49]
	v_mfma_f32_16x16x32_bf16 v[42:45], v[156:159], v[198:201], v[42:45]
	v_mfma_f32_16x16x32_bf16 v[30:33], v[134:137], v[206:209], v[30:33]
	v_mfma_f32_16x16x32_bf16 v[26:29], v[156:159], v[206:209], v[26:29]
	v_mfma_f32_16x16x32_bf16 v[12:15], v[134:137], v[214:217], v[12:15]
	v_mfma_f32_16x16x32_bf16 v[8:11], v[156:159], v[214:217], v[8:11]
	v_mfma_f32_16x16x32_bf16 v[54:57], v[160:163], v[186:189], v[54:57]
	v_mfma_f32_16x16x32_bf16 v[50:53], v[178:181], v[186:189], v[50:53]
	v_mfma_f32_16x16x32_bf16 v[38:41], v[160:163], v[194:197], v[38:41]
	v_mfma_f32_16x16x32_bf16 v[34:37], v[178:181], v[194:197], v[34:37]
	v_mfma_f32_16x16x32_bf16 v[22:25], v[160:163], v[202:205], v[22:25]
	v_mfma_f32_16x16x32_bf16 v[18:21], v[178:181], v[202:205], v[18:21]
	v_mfma_f32_16x16x32_bf16 v[4:7], v[160:163], v[210:213], v[4:7]
	v_mfma_f32_16x16x32_bf16 v[0:3], v[178:181], v[210:213], v[0:3]
	v_mfma_f32_16x16x32_bf16 v[54:57], v[174:177], v[190:193], v[54:57]
	v_mfma_f32_16x16x32_bf16 v[50:53], v[182:185], v[190:193], v[50:53]
	v_mfma_f32_16x16x32_bf16 v[38:41], v[174:177], v[198:201], v[38:41]
	v_mfma_f32_16x16x32_bf16 v[34:37], v[182:185], v[198:201], v[34:37]
	v_mfma_f32_16x16x32_bf16 v[22:25], v[174:177], v[206:209], v[22:25]
	v_mfma_f32_16x16x32_bf16 v[18:21], v[182:185], v[206:209], v[18:21]
	v_mfma_f32_16x16x32_bf16 v[4:7], v[174:177], v[214:217], v[4:7]
	v_mfma_f32_16x16x32_bf16 v[0:3], v[182:185], v[214:217], v[0:3]
	s_barrier
; #define PG8_STAGEA(bufoff, gbase, voff) PG8_STAGE_X(bufoff, gbase, voff, AUXA)
; #define PG8_STAGEB(bufoff, gbase, voff) PG8_STAGE_X(bufoff, gbase, voff, AUXB)
; #define PG8_LDA(dst, b, h) do { _Pragma("unroll") for (int m = 0; m < 4; ++m) _Pragma("unroll") for (int k = 0; k < 2; ++k) dst[m][k] = *(const PG8_LAS bf16x8*)(lds + PG8_SA(b, h) + aoff + m * 2048 + k * 1024); } while (0)
; #define PG8_LDB(dst, b, h) do { _Pragma("unroll") for (int n = 0; n < 2; ++n) _Pragma("unroll") for (int k = 0; k < 2; ++k) dst[n][k] = *(const PG8_LAS bf16x8*)(lds + PG8_SB(b, h) + boff + n * 2048 + k * 1024); } while (0)
; #define PG8_MMA(ai, bj, At, Bt) do { if (GEMM_PRIO_MODE == 0) __builtin_amdgcn_s_setprio(1); PG8_MMA_LOOPS \
;         acc[ai][bj][m][n] = __builtin_amdgcn_mfma_f32_16x16x32_bf16(Bt[n][k], At[m][k], acc[ai][bj][m][n], 0, 0, 0); if (GEMM_PRIO_MODE == 0) __builtin_amdgcn_s_setprio(0); } while (0)
; #define PG8_WAIT_V(n) asm volatile("s_waitcnt vmcnt(" #n ")" ::: "memory")
;     ...
;             PG8_LDB(B0, 0, 0); PG8_LDB(B1, 0, 1); PG8_SCHED; PG8_LDA(At, 0, 0); PG8_STAGEA(PG8_SA(1, 1), a1 + hstepA, voffA);
;     ...
;             const int relax = __builtin_amdgcn_readfirstlane((t == 0 && ui > 0) ? 1 : 0);
;             PG8_WAIT_VR(8, 24, relax); PG8_WAIT_L(0); PG8_BAR; PG8_MMA(0, 0, At, B0); PG8_MMA(0, 1, At, B1); PG8_BAR; PG8_SCHED;
;     ...
;             PG8_WAIT_V(8); PG8_WAIT_L(0); PG8_BAR; PG8_MMA(0, 0, At, B0); PG8_MMA(0, 1, At, B1); PG8_BAR; PG8_SCHED;
;     ...
;             PG8_LDA(At, 0, 1); PG8_STAGEB(PG8_SB(0, 0), b2, voffB); PG8_STAGEB(PG8_SB(0, 1), b2 + hstepB, voffB); PG8_STAGEA(PG8_SA(0, 0), a2, voffA);
;     ...
;             PG8_WAIT_VR(8, 24, relax); PG8_WAIT_L(0); PG8_BAR; PG8_MMA(1, 0, At, B0); PG8_MMA(1, 1, At, B1); PG8_BAR; PG8_SCHED;
;     ...
;             PG8_WAIT_V(8); PG8_WAIT_L(0); PG8_BAR; PG8_MMA(1, 0, At, B0); PG8_MMA(1, 1, At, B1); PG8_BAR; PG8_SCHED;
;     ...
;             PG8_LDB(B0, 1, 0); PG8_LDB(B1, 1, 1); PG8_SCHED; PG8_LDA(At, 1, 0); PG8_STAGEA(PG8_SA(0, 1), a2 + hstepA, voffA);
;             PG8_WAIT_V(8); PG8_WAIT_L(0); PG8_BAR; PG8_MMA(0, 0, At, B0); PG8_MMA(0, 1, At, B1); PG8_BAR; PG8_SCHED;
;             PG8_LDA(At, 1, 1); PG8_STAGEB(PG8_SB(1, 0), b3, voffB); PG8_STAGEB(PG8_SB(1, 1), b3 + hstepB, voffB); PG8_STAGEA(PG8_SA(1, 0), a3, voffA);
;             PG8_WAIT_V(8); PG8_WAIT_L(0); PG8_BAR; PG8_MMA(1, 0, At, B0); PG8_MMA(1, 1, At, B1); PG8_BAR; PG8_SCHED;
	ds_read_b128 v[130:133], v226 offset:32768
	ds_read_b128 v[134:137], v226 offset:33792
	ds_read_b128 v[152:155], v226 offset:34816
	ds_read_b128 v[156:159], v226 offset:35840
	ds_read_b128 v[160:163], v226 offset:49152
	ds_read_b128 v[174:177], v226 offset:50176
	ds_read_b128 v[178:181], v226 offset:51200
	ds_read_b128 v[182:185], v226 offset:52224
	s_add_u32 s14, s14, 0x100000
	s_addc_u32 s15, s15, 0
	s_mov_b32 m0, s69
	ds_read_b128 v[186:189], v172 offset:32768
	ds_read_b128 v[190:193], v172 offset:33792
	ds_read_b128 v[194:197], v172 offset:34816
	ds_read_b128 v[198:201], v172 offset:35840
	ds_read_b128 v[202:205], v172 offset:36864
	ds_read_b128 v[206:209], v172 offset:37888
	ds_read_b128 v[210:213], v172 offset:38912
	global_load_lds_dwordx4 v144, s[14:15]
	s_mov_b32 m0, s72
	ds_read_b128 v[214:217], v172 offset:39936
	global_load_lds_dwordx4 v140, s[14:15]
	s_waitcnt vmcnt(8) lgkmcnt(0)
	s_nop 0
	s_nop 0
	s_barrier
	v_mfma_f32_16x16x32_bf16 v[126:129], v[130:133], v[186:189], v[126:129]
	v_mfma_f32_16x16x32_bf16 v[122:125], v[152:155], v[186:189], v[122:125]
	v_mfma_f32_16x16x32_bf16 v[110:113], v[130:133], v[194:197], v[110:113]
	v_mfma_f32_16x16x32_bf16 v[106:109], v[152:155], v[194:197], v[106:109]
	v_mfma_f32_16x16x32_bf16 v[94:97], v[130:133], v[202:205], v[94:97]
	v_mfma_f32_16x16x32_bf16 v[90:93], v[152:155], v[202:205], v[90:93]
	v_mfma_f32_16x16x32_bf16 v[78:81], v[130:133], v[210:213], v[78:81]
	v_mfma_f32_16x16x32_bf16 v[74:77], v[152:155], v[210:213], v[74:77]
	v_mfma_f32_16x16x32_bf16 v[126:129], v[134:137], v[190:193], v[126:129]
	v_mfma_f32_16x16x32_bf16 v[122:125], v[156:159], v[190:193], v[122:125]
	v_mfma_f32_16x16x32_bf16 v[110:113], v[134:137], v[198:201], v[110:113]
	v_mfma_f32_16x16x32_bf16 v[106:109], v[156:159], v[198:201], v[106:109]
	v_mfma_f32_16x16x32_bf16 v[94:97], v[134:137], v[206:209], v[94:97]
	v_mfma_f32_16x16x32_bf16 v[90:93], v[156:159], v[206:209], v[90:93]
	v_mfma_f32_16x16x32_bf16 v[78:81], v[134:137], v[214:217], v[78:81]
	v_mfma_f32_16x16x32_bf16 v[74:77], v[156:159], v[214:217], v[74:77]
	v_mfma_f32_16x16x32_bf16 v[118:121], v[160:163], v[186:189], v[118:121]
	v_mfma_f32_16x16x32_bf16 v[114:117], v[178:181], v[186:189], v[114:117]
	v_mfma_f32_16x16x32_bf16 v[102:105], v[160:163], v[194:197], v[102:105]
	v_mfma_f32_16x16x32_bf16 v[98:101], v[178:181], v[194:197], v[98:101]
	v_mfma_f32_16x16x32_bf16 v[86:89], v[160:163], v[202:205], v[86:89]
	v_mfma_f32_16x16x32_bf16 v[82:85], v[178:181], v[202:205], v[82:85]
	v_mfma_f32_16x16x32_bf16 v[70:73], v[160:163], v[210:213], v[70:73]
	v_mfma_f32_16x16x32_bf16 v[66:69], v[178:181], v[210:213], v[66:69]
	v_mfma_f32_16x16x32_bf16 v[118:121], v[174:177], v[190:193], v[118:121]
	v_mfma_f32_16x16x32_bf16 v[114:117], v[182:185], v[190:193], v[114:117]
	v_mfma_f32_16x16x32_bf16 v[102:105], v[174:177], v[198:201], v[102:105]
	v_mfma_f32_16x16x32_bf16 v[98:101], v[182:185], v[198:201], v[98:101]
	v_mfma_f32_16x16x32_bf16 v[86:89], v[174:177], v[206:209], v[86:89]
	v_mfma_f32_16x16x32_bf16 v[82:85], v[182:185], v[206:209], v[82:85]
	v_mfma_f32_16x16x32_bf16 v[70:73], v[174:177], v[214:217], v[70:73]
	v_mfma_f32_16x16x32_bf16 v[66:69], v[182:185], v[214:217], v[66:69]
	s_barrier
	s_add_i32 s14, s42, 0x18000
	s_mov_b32 m0, s14
	ds_read_b128 v[186:189], v172 offset:49152
	ds_read_b128 v[190:193], v172 offset:50176
	ds_read_b128 v[194:197], v172 offset:51200
	ds_read_b128 v[198:201], v172 offset:52224
	s_add_u32 vcc_lo, s10, 0x80
	s_addc_u32 vcc_hi, s11, 0
	global_load_lds_dwordx4 v142, vcc
	s_add_i32 m0, s14, 0x2000
	s_add_u32 s10, s10, 0x100080
	s_addc_u32 s11, s11, 0
	s_add_i32 s14, s42, 0x1c000
	global_load_lds_dwordx4 v138, vcc
	s_mov_b32 m0, s14
	ds_read_b128 v[214:217], v172 offset:56320
	global_load_lds_dwordx4 v142, s[10:11]
	s_add_i32 m0, s14, 0x2000
	ds_read_b128 v[210:213], v172 offset:55296
	global_load_lds_dwordx4 v138, s[10:11]
	s_mov_b32 m0, s73
	ds_read_b128 v[206:209], v172 offset:54272
	global_load_lds_dwordx4 v144, s[100:101]
	s_mov_b32 m0, s82
	ds_read_b128 v[202:205], v172 offset:53248
	global_load_lds_dwordx4 v140, s[100:101]
	s_waitcnt vmcnt(8) lgkmcnt(0)
	s_nop 0
	s_barrier
	v_mfma_f32_16x16x32_bf16 v[62:65], v[130:133], v[186:189], v[62:65]
	v_mfma_f32_16x16x32_bf16 v[58:61], v[152:155], v[186:189], v[58:61]
	v_mfma_f32_16x16x32_bf16 v[46:49], v[130:133], v[194:197], v[46:49]
	v_mfma_f32_16x16x32_bf16 v[42:45], v[152:155], v[194:197], v[42:45]
	v_mfma_f32_16x16x32_bf16 v[30:33], v[130:133], v[202:205], v[30:33]
	v_mfma_f32_16x16x32_bf16 v[26:29], v[152:155], v[202:205], v[26:29]
	v_mfma_f32_16x16x32_bf16 v[12:15], v[130:133], v[210:213], v[12:15]
	v_mfma_f32_16x16x32_bf16 v[8:11], v[152:155], v[210:213], v[8:11]
	v_mfma_f32_16x16x32_bf16 v[62:65], v[134:137], v[190:193], v[62:65]
	v_mfma_f32_16x16x32_bf16 v[58:61], v[156:159], v[190:193], v[58:61]
	v_mfma_f32_16x16x32_bf16 v[46:49], v[134:137], v[198:201], v[46:49]
	v_mfma_f32_16x16x32_bf16 v[42:45], v[156:159], v[198:201], v[42:45]
	v_mfma_f32_16x16x32_bf16 v[30:33], v[134:137], v[206:209], v[30:33]
	v_mfma_f32_16x16x32_bf16 v[26:29], v[156:159], v[206:209], v[26:29]
	v_mfma_f32_16x16x32_bf16 v[12:15], v[134:137], v[214:217], v[12:15]
	v_mfma_f32_16x16x32_bf16 v[8:11], v[156:159], v[214:217], v[8:11]
	v_mfma_f32_16x16x32_bf16 v[54:57], v[160:163], v[186:189], v[54:57]
	v_mfma_f32_16x16x32_bf16 v[50:53], v[178:181], v[186:189], v[50:53]
	v_mfma_f32_16x16x32_bf16 v[38:41], v[160:163], v[194:197], v[38:41]
	v_mfma_f32_16x16x32_bf16 v[34:37], v[178:181], v[194:197], v[34:37]
	v_mfma_f32_16x16x32_bf16 v[22:25], v[160:163], v[202:205], v[22:25]
	v_mfma_f32_16x16x32_bf16 v[18:21], v[178:181], v[202:205], v[18:21]
	v_mfma_f32_16x16x32_bf16 v[4:7], v[160:163], v[210:213], v[4:7]
	v_mfma_f32_16x16x32_bf16 v[0:3], v[178:181], v[210:213], v[0:3]
	v_mfma_f32_16x16x32_bf16 v[54:57], v[174:177], v[190:193], v[54:57]
	v_mfma_f32_16x16x32_bf16 v[50:53], v[182:185], v[190:193], v[50:53]
	v_mfma_f32_16x16x32_bf16 v[38:41], v[174:177], v[198:201], v[38:41]
	v_mfma_f32_16x16x32_bf16 v[34:37], v[182:185], v[198:201], v[34:37]
	v_mfma_f32_16x16x32_bf16 v[22:25], v[174:177], v[206:209], v[22:25]
	v_mfma_f32_16x16x32_bf16 v[18:21], v[182:185], v[206:209], v[18:21]
	v_mfma_f32_16x16x32_bf16 v[4:7], v[174:177], v[214:217], v[4:7]
	v_mfma_f32_16x16x32_bf16 v[0:3], v[182:185], v[214:217], v[0:3]
	s_barrier
	s_add_i32 s27, s27, 2
	s_add_u32 s8, s8, 0x100
	s_addc_u32 s9, s9, 0
	s_add_u32 s0, s0, 0x100
	s_addc_u32 s1, s1, 0
	s_cmp_gt_u32 s27, 61
	s_cbranch_scc0 .LBB0_129
	s_and_b64 vcc, exec, s[24:25]
	s_cbranch_vccz .LBB0_132
	s_barrier

; #define PG8_STAGEA(bufoff, gbase, voff) PG8_STAGE_X(bufoff, gbase, voff, AUXA)
; #define PG8_STAGEB(bufoff, gbase, voff) PG8_STAGE_X(bufoff, gbase, voff, AUXB)
; #define PG8_LDA(dst, b, h) do { _Pragma("unroll") for (int m = 0; m < 4; ++m) _Pragma("unroll") for (int k = 0; k < 2; ++k) dst[m][k] = *(const PG8_LAS bf16x8*)(lds + PG8_SA(b, h) + aoff + m * 2048 + k * 1024); } while (0)
; #define PG8_WAIT_V(n) asm volatile("s_waitcnt vmcnt(" #n ")" ::: "memory")
; #define PG8_WAIT_L(n) asm volatile("s_waitcnt lgkmcnt(" #n ")" ::: "memory")
;     ...
;         for (int t = t0; t < nt; t += 2) {
;             const bool last = (t == nt - 2);
;             const char* a1 = cA + (size_t)(t + 1) * kstepA;
;             const char* a2 = last ? nA : cA + (size_t)(t + 2) * kstepA; const char* b2 = last ? nB : cB + (size_t)(t + 2) * kstepB;
;             const char* a3 = a2 + kstepA; const char* b3 = b2 + kstepB;
;             if (last && has_next) S.a_ready(nxt);
;             if constexpr (SP2) {
;             PG8_LDB(B0, 0, 0); PG8_LDB(B1, 0, 1); PG8_SCHED; PG8_LDA(At, 0, 0); PG8_STAGEA(PG8_SA(1, 1), a1 + hstepA, voffA);
;     ...
;             const int relax = __builtin_amdgcn_readfirstlane((t == 0 && ui > 0) ? 1 : 0);
;             PG8_WAIT_VR(8, 24, relax); PG8_WAIT_L(0); PG8_BAR; PG8_MMA(0, 0, At, B0); PG8_MMA(0, 1, At, B1); PG8_BAR; PG8_SCHED;
;     ...
;             PG8_WAIT_V(8); PG8_WAIT_L(0); PG8_BAR; PG8_MMA(0, 0, At, B0); PG8_MMA(0, 1, At, B1); PG8_BAR; PG8_SCHED;
;     ...
;             PG8_LDA(At, 0, 1); PG8_STAGEB(PG8_SB(0, 0), b2, voffB); PG8_STAGEB(PG8_SB(0, 1), b2 + hstepB, voffB); PG8_STAGEA(PG8_SA(0, 0), a2, voffA);
;     ...
;             PG8_WAIT_VR(8, 24, relax); PG8_WAIT_L(0); PG8_BAR; PG8_MMA(1, 0, At, B0); PG8_MMA(1, 1, At, B1); PG8_BAR; PG8_SCHED;
;     ...
;             PG8_WAIT_V(8); PG8_WAIT_L(0); PG8_BAR; PG8_MMA(1, 0, At, B0); PG8_MMA(1, 1, At, B1); PG8_BAR; PG8_SCHED;
;     ...
;             PG8_LDB(B0, 1, 0); PG8_LDB(B1, 1, 1); PG8_SCHED; PG8_LDA(At, 1, 0); PG8_STAGEA(PG8_SA(0, 1), a2 + hstepA, voffA);
;             PG8_WAIT_V(8); PG8_WAIT_L(0); PG8_BAR; PG8_MMA(0, 0, At, B0); PG8_MMA(0, 1, At, B1); PG8_BAR; PG8_SCHED;
;             PG8_LDA(At, 1, 1); PG8_STAGEB(PG8_SB(1, 0), b3, voffB); PG8_STAGEB(PG8_SB(1, 1), b3 + hstepB, voffB); PG8_STAGEA(PG8_SA(1, 0), a3, voffA);
;             PG8_WAIT_V(8); PG8_WAIT_L(0); PG8_BAR; PG8_MMA(1, 0, At, B0); PG8_MMA(1, 1, At, B1); PG8_BAR; PG8_SCHED;
.LBB0_558:
	s_add_u32 s6, s38, 0xfff00080
	s_addc_u32 s7, s39, -1
	s_cmp_eq_u32 s90, 60
	s_cselect_b32 s41, s21, s7
	s_cselect_b32 s40, s82, s6
	s_cselect_b32 s17, s23, s1
	s_cselect_b32 s16, s83, s0
	ds_read_b128 v[130:133], v220
	ds_read_b128 v[134:137], v220 offset:1024
	ds_read_b128 v[148:151], v220 offset:2048
	ds_read_b128 v[152:155], v220 offset:3072
	ds_read_b128 v[162:165], v220 offset:16384
	ds_read_b128 v[166:169], v220 offset:17408
	ds_read_b128 v[170:173], v220 offset:18432
	ds_read_b128 v[174:177], v220 offset:19456
	s_add_i32 m0, s13, 0xc000
	ds_read_b128 v[178:181], v161
	ds_read_b128 v[182:185], v161 offset:1024
	ds_read_b128 v[186:189], v161 offset:2048
	ds_read_b128 v[190:193], v161 offset:3072
	ds_read_b128 v[194:197], v161 offset:4096
	ds_read_b128 v[198:201], v161 offset:5120
	ds_read_b128 v[202:205], v161 offset:6144
	global_load_lds_dwordx4 v144, s[38:39]
	s_add_i32 m0, s13, 0xe000
	ds_read_b128 v[206:209], v161 offset:7168
	global_load_lds_dwordx4 v146, s[38:39]
	s_waitcnt vmcnt(8) lgkmcnt(0)
	s_barrier
	v_mfma_f32_16x16x32_bf16 v[126:129], v[130:133], v[178:181], v[126:129]
	v_mfma_f32_16x16x32_bf16 v[122:125], v[148:151], v[178:181], v[122:125]
	v_mfma_f32_16x16x32_bf16 v[110:113], v[130:133], v[186:189], v[110:113]
	v_mfma_f32_16x16x32_bf16 v[106:109], v[148:151], v[186:189], v[106:109]
	v_mfma_f32_16x16x32_bf16 v[94:97], v[130:133], v[194:197], v[94:97]
	v_mfma_f32_16x16x32_bf16 v[90:93], v[148:151], v[194:197], v[90:93]
	v_mfma_f32_16x16x32_bf16 v[78:81], v[130:133], v[202:205], v[78:81]
	v_mfma_f32_16x16x32_bf16 v[74:77], v[148:151], v[202:205], v[74:77]
	v_mfma_f32_16x16x32_bf16 v[126:129], v[134:137], v[182:185], v[126:129]
	v_mfma_f32_16x16x32_bf16 v[122:125], v[152:155], v[182:185], v[122:125]
	v_mfma_f32_16x16x32_bf16 v[110:113], v[134:137], v[190:193], v[110:113]
	v_mfma_f32_16x16x32_bf16 v[106:109], v[152:155], v[190:193], v[106:109]
	v_mfma_f32_16x16x32_bf16 v[94:97], v[134:137], v[198:201], v[94:97]
	v_mfma_f32_16x16x32_bf16 v[90:93], v[152:155], v[198:201], v[90:93]
	v_mfma_f32_16x16x32_bf16 v[78:81], v[134:137], v[206:209], v[78:81]
	v_mfma_f32_16x16x32_bf16 v[74:77], v[152:155], v[206:209], v[74:77]
	v_mfma_f32_16x16x32_bf16 v[118:121], v[162:165], v[178:181], v[118:121]
	v_mfma_f32_16x16x32_bf16 v[114:117], v[170:173], v[178:181], v[114:117]
	v_mfma_f32_16x16x32_bf16 v[102:105], v[162:165], v[186:189], v[102:105]
	v_mfma_f32_16x16x32_bf16 v[98:101], v[170:173], v[186:189], v[98:101]
	v_mfma_f32_16x16x32_bf16 v[86:89], v[162:165], v[194:197], v[86:89]
	v_mfma_f32_16x16x32_bf16 v[82:85], v[170:173], v[194:197], v[82:85]
	v_mfma_f32_16x16x32_bf16 v[70:73], v[162:165], v[202:205], v[70:73]
	v_mfma_f32_16x16x32_bf16 v[66:69], v[170:173], v[202:205], v[66:69]
	v_mfma_f32_16x16x32_bf16 v[118:121], v[166:169], v[182:185], v[118:121]
	v_mfma_f32_16x16x32_bf16 v[114:117], v[174:177], v[182:185], v[114:117]
	v_mfma_f32_16x16x32_bf16 v[102:105], v[166:169], v[190:193], v[102:105]
	v_mfma_f32_16x16x32_bf16 v[98:101], v[174:177], v[190:193], v[98:101]
	v_mfma_f32_16x16x32_bf16 v[86:89], v[166:169], v[198:201], v[86:89]
	v_mfma_f32_16x16x32_bf16 v[82:85], v[174:177], v[198:201], v[82:85]
	v_mfma_f32_16x16x32_bf16 v[70:73], v[166:169], v[206:209], v[70:73]
	v_mfma_f32_16x16x32_bf16 v[66:69], v[174:177], v[206:209], v[66:69]
	s_barrier
	s_add_i32 s6, s12, 0x10000
	s_mov_b32 m0, s6
	ds_read_b128 v[178:181], v161 offset:16384
	ds_read_b128 v[182:185], v161 offset:17408
	ds_read_b128 v[186:189], v161 offset:18432
	ds_read_b128 v[190:193], v161 offset:19456
	global_load_lds_dwordx4 v16, s[16:17]
	s_add_i32 m0, s6, 0x2000
	s_add_u32 s6, s16, 0x100000
	s_addc_u32 s7, s17, 0
	s_add_i32 s91, s12, 0x14000
	global_load_lds_dwordx4 v138, s[16:17]
	s_mov_b32 m0, s91
	ds_read_b128 v[206:209], v161 offset:23552
	global_load_lds_dwordx4 v16, s[6:7]
	s_add_i32 m0, s91, 0x2000
	ds_read_b128 v[202:205], v161 offset:22528
	global_load_lds_dwordx4 v138, s[6:7]
	s_mov_b32 m0, s13
	ds_read_b128 v[198:201], v161 offset:21504
	global_load_lds_dwordx4 v142, s[40:41]
	s_mov_b32 m0, s42
	ds_read_b128 v[194:197], v161 offset:20480
	global_load_lds_dwordx4 v140, s[40:41]
	s_waitcnt vmcnt(8) lgkmcnt(0)
	s_barrier
	v_mfma_f32_16x16x32_bf16 v[62:65], v[130:133], v[178:181], v[62:65]
	v_mfma_f32_16x16x32_bf16 v[58:61], v[148:151], v[178:181], v[58:61]
	v_mfma_f32_16x16x32_bf16 v[46:49], v[130:133], v[186:189], v[46:49]
	v_mfma_f32_16x16x32_bf16 v[42:45], v[148:151], v[186:189], v[42:45]
	v_mfma_f32_16x16x32_bf16 v[30:33], v[130:133], v[194:197], v[30:33]
	v_mfma_f32_16x16x32_bf16 v[26:29], v[148:151], v[194:197], v[26:29]
	v_mfma_f32_16x16x32_bf16 v[12:15], v[130:133], v[202:205], v[12:15]
	v_mfma_f32_16x16x32_bf16 v[8:11], v[148:151], v[202:205], v[8:11]
	v_mfma_f32_16x16x32_bf16 v[62:65], v[134:137], v[182:185], v[62:65]
	v_mfma_f32_16x16x32_bf16 v[58:61], v[152:155], v[182:185], v[58:61]
	v_mfma_f32_16x16x32_bf16 v[46:49], v[134:137], v[190:193], v[46:49]
	v_mfma_f32_16x16x32_bf16 v[42:45], v[152:155], v[190:193], v[42:45]
	v_mfma_f32_16x16x32_bf16 v[30:33], v[134:137], v[198:201], v[30:33]
	v_mfma_f32_16x16x32_bf16 v[26:29], v[152:155], v[198:201], v[26:29]
	v_mfma_f32_16x16x32_bf16 v[12:15], v[134:137], v[206:209], v[12:15]
	v_mfma_f32_16x16x32_bf16 v[8:11], v[152:155], v[206:209], v[8:11]
	v_mfma_f32_16x16x32_bf16 v[54:57], v[162:165], v[178:181], v[54:57]
	v_mfma_f32_16x16x32_bf16 v[50:53], v[170:173], v[178:181], v[50:53]
	v_mfma_f32_16x16x32_bf16 v[38:41], v[162:165], v[186:189], v[38:41]
	v_mfma_f32_16x16x32_bf16 v[34:37], v[170:173], v[186:189], v[34:37]
	v_mfma_f32_16x16x32_bf16 v[22:25], v[162:165], v[194:197], v[22:25]
	v_mfma_f32_16x16x32_bf16 v[18:21], v[170:173], v[194:197], v[18:21]
	v_mfma_f32_16x16x32_bf16 v[4:7], v[162:165], v[202:205], v[4:7]
	v_mfma_f32_16x16x32_bf16 v[0:3], v[170:173], v[202:205], v[0:3]
	v_mfma_f32_16x16x32_bf16 v[54:57], v[166:169], v[182:185], v[54:57]
	v_mfma_f32_16x16x32_bf16 v[50:53], v[174:177], v[182:185], v[50:53]
	v_mfma_f32_16x16x32_bf16 v[38:41], v[166:169], v[190:193], v[38:41]
	v_mfma_f32_16x16x32_bf16 v[34:37], v[174:177], v[190:193], v[34:37]
	v_mfma_f32_16x16x32_bf16 v[22:25], v[166:169], v[198:201], v[22:25]
	v_mfma_f32_16x16x32_bf16 v[18:21], v[174:177], v[198:201], v[18:21]
	v_mfma_f32_16x16x32_bf16 v[4:7], v[166:169], v[206:209], v[4:7]
	v_mfma_f32_16x16x32_bf16 v[0:3], v[174:177], v[206:209], v[0:3]
	s_barrier
; #define PG8_STAGEA(bufoff, gbase, voff) PG8_STAGE_X(bufoff, gbase, voff, AUXA)
; #define PG8_STAGEB(bufoff, gbase, voff) PG8_STAGE_X(bufoff, gbase, voff, AUXB)
; #define PG8_LDA(dst, b, h) do { _Pragma("unroll") for (int m = 0; m < 4; ++m) _Pragma("unroll") for (int k = 0; k < 2; ++k) dst[m][k] = *(const PG8_LAS bf16x8*)(lds + PG8_SA(b, h) + aoff + m * 2048 + k * 1024); } while (0)
; #define PG8_LDB(dst, b, h) do { _Pragma("unroll") for (int n = 0; n < 2; ++n) _Pragma("unroll") for (int k = 0; k < 2; ++k) dst[n][k] = *(const PG8_LAS bf16x8*)(lds + PG8_SB(b, h) + boff + n * 2048 + k * 1024); } while (0)
; #define PG8_MMA(ai, bj, At, Bt) do { if (GEMM_PRIO_MODE == 0) __builtin_amdgcn_s_setprio(1); PG8_MMA_LOOPS \
;         acc[ai][bj][m][n] = __builtin_amdgcn_mfma_f32_16x16x32_bf16(Bt[n][k], At[m][k], acc[ai][bj][m][n], 0, 0, 0); if (GEMM_PRIO_MODE == 0) __builtin_amdgcn_s_setprio(0); } while (0)
; #define PG8_WAIT_V(n) asm volatile("s_waitcnt vmcnt(" #n ")" ::: "memory")
;     ...
;             PG8_LDB(B0, 0, 0); PG8_LDB(B1, 0, 1); PG8_SCHED; PG8_LDA(At, 0, 0); PG8_STAGEA(PG8_SA(1, 1), a1 + hstepA, voffA);
;     ...
;             const int relax = __builtin_amdgcn_readfirstlane((t == 0 && ui > 0) ? 1 : 0);
;             PG8_WAIT_VR(8, 24, relax); PG8_WAIT_L(0); PG8_BAR; PG8_MMA(0, 0, At, B0); PG8_MMA(0, 1, At, B1); PG8_BAR; PG8_SCHED;
;     ...
;             PG8_WAIT_V(8); PG8_WAIT_L(0); PG8_BAR; PG8_MMA(0, 0, At, B0); PG8_MMA(0, 1, At, B1); PG8_BAR; PG8_SCHED;
;     ...
;             PG8_LDA(At, 0, 1); PG8_STAGEB(PG8_SB(0, 0), b2, voffB); PG8_STAGEB(PG8_SB(0, 1), b2 + hstepB, voffB); PG8_STAGEA(PG8_SA(0, 0), a2, voffA);
;     ...
;             PG8_WAIT_VR(8, 24, relax); PG8_WAIT_L(0); PG8_BAR; PG8_MMA(1, 0, At, B0); PG8_MMA(1, 1, At, B1); PG8_BAR; PG8_SCHED;
;     ...
;             PG8_WAIT_V(8); PG8_WAIT_L(0); PG8_BAR; PG8_MMA(1, 0, At, B0); PG8_MMA(1, 1, At, B1); PG8_BAR; PG8_SCHED;
;     ...
;             PG8_LDB(B0, 1, 0); PG8_LDB(B1, 1, 1); PG8_SCHED; PG8_LDA(At, 1, 0); PG8_STAGEA(PG8_SA(0, 1), a2 + hstepA, voffA);
;             PG8_WAIT_V(8); PG8_WAIT_L(0); PG8_BAR; PG8_MMA(0, 0, At, B0); PG8_MMA(0, 1, At, B1); PG8_BAR; PG8_SCHED;
;             PG8_LDA(At, 1, 1); PG8_STAGEB(PG8_SB(1, 0), b3, voffB); PG8_STAGEB(PG8_SB(1, 1), b3 + hstepB, voffB); PG8_STAGEA(PG8_SA(1, 0), a3, voffA);
;             PG8_WAIT_V(8); PG8_WAIT_L(0); PG8_BAR; PG8_MMA(1, 0, At, B0); PG8_MMA(1, 1, At, B1); PG8_BAR; PG8_SCHED;
	ds_read_b128 v[130:133], v220 offset:32768
	ds_read_b128 v[134:137], v220 offset:33792
	ds_read_b128 v[148:151], v220 offset:34816
	ds_read_b128 v[152:155], v220 offset:35840
	ds_read_b128 v[162:165], v220 offset:49152
	ds_read_b128 v[166:169], v220 offset:50176
	ds_read_b128 v[170:173], v220 offset:51200
	ds_read_b128 v[174:177], v220 offset:52224
	s_add_u32 s6, s40, 0x100000
	s_addc_u32 s7, s41, 0
	s_mov_b32 m0, s43
	ds_read_b128 v[178:181], v161 offset:32768
	ds_read_b128 v[182:185], v161 offset:33792
	ds_read_b128 v[186:189], v161 offset:34816
	ds_read_b128 v[190:193], v161 offset:35840
	ds_read_b128 v[194:197], v161 offset:36864
	ds_read_b128 v[198:201], v161 offset:37888
	ds_read_b128 v[202:205], v161 offset:38912
	global_load_lds_dwordx4 v142, s[6:7]
	s_mov_b32 m0, s50
	ds_read_b128 v[206:209], v161 offset:39936
	global_load_lds_dwordx4 v140, s[6:7]
	s_waitcnt vmcnt(8) lgkmcnt(0)
	s_barrier
	v_mfma_f32_16x16x32_bf16 v[126:129], v[130:133], v[178:181], v[126:129]
	v_mfma_f32_16x16x32_bf16 v[122:125], v[148:151], v[178:181], v[122:125]
	v_mfma_f32_16x16x32_bf16 v[110:113], v[130:133], v[186:189], v[110:113]
	v_mfma_f32_16x16x32_bf16 v[106:109], v[148:151], v[186:189], v[106:109]
	v_mfma_f32_16x16x32_bf16 v[94:97], v[130:133], v[194:197], v[94:97]
	v_mfma_f32_16x16x32_bf16 v[90:93], v[148:151], v[194:197], v[90:93]
	v_mfma_f32_16x16x32_bf16 v[78:81], v[130:133], v[202:205], v[78:81]
	v_mfma_f32_16x16x32_bf16 v[74:77], v[148:151], v[202:205], v[74:77]
	v_mfma_f32_16x16x32_bf16 v[126:129], v[134:137], v[182:185], v[126:129]
	v_mfma_f32_16x16x32_bf16 v[122:125], v[152:155], v[182:185], v[122:125]
	v_mfma_f32_16x16x32_bf16 v[110:113], v[134:137], v[190:193], v[110:113]
	v_mfma_f32_16x16x32_bf16 v[106:109], v[152:155], v[190:193], v[106:109]
	v_mfma_f32_16x16x32_bf16 v[94:97], v[134:137], v[198:201], v[94:97]
	v_mfma_f32_16x16x32_bf16 v[90:93], v[152:155], v[198:201], v[90:93]
	v_mfma_f32_16x16x32_bf16 v[78:81], v[134:137], v[206:209], v[78:81]
	v_mfma_f32_16x16x32_bf16 v[74:77], v[152:155], v[206:209], v[74:77]
	v_mfma_f32_16x16x32_bf16 v[118:121], v[162:165], v[178:181], v[118:121]
	v_mfma_f32_16x16x32_bf16 v[114:117], v[170:173], v[178:181], v[114:117]
	v_mfma_f32_16x16x32_bf16 v[102:105], v[162:165], v[186:189], v[102:105]
	v_mfma_f32_16x16x32_bf16 v[98:101], v[170:173], v[186:189], v[98:101]
	v_mfma_f32_16x16x32_bf16 v[86:89], v[162:165], v[194:197], v[86:89]
	v_mfma_f32_16x16x32_bf16 v[82:85], v[170:173], v[194:197], v[82:85]
	v_mfma_f32_16x16x32_bf16 v[70:73], v[162:165], v[202:205], v[70:73]
	v_mfma_f32_16x16x32_bf16 v[66:69], v[170:173], v[202:205], v[66:69]
	v_mfma_f32_16x16x32_bf16 v[118:121], v[166:169], v[182:185], v[118:121]
	v_mfma_f32_16x16x32_bf16 v[114:117], v[174:177], v[182:185], v[114:117]
	v_mfma_f32_16x16x32_bf16 v[102:105], v[166:169], v[190:193], v[102:105]
	v_mfma_f32_16x16x32_bf16 v[98:101], v[174:177], v[190:193], v[98:101]
	v_mfma_f32_16x16x32_bf16 v[86:89], v[166:169], v[198:201], v[86:89]
	v_mfma_f32_16x16x32_bf16 v[82:85], v[174:177], v[198:201], v[82:85]
	v_mfma_f32_16x16x32_bf16 v[70:73], v[166:169], v[206:209], v[70:73]
	v_mfma_f32_16x16x32_bf16 v[66:69], v[174:177], v[206:209], v[66:69]
	s_barrier
	s_add_i32 s6, s12, 0x18000
	s_mov_b32 m0, s6
	ds_read_b128 v[178:181], v161 offset:49152
	ds_read_b128 v[182:185], v161 offset:50176
	ds_read_b128 v[186:189], v161 offset:51200
	ds_read_b128 v[190:193], v161 offset:52224
	ds_read_b128 v[194:197], v161 offset:53248
	s_add_u32 s100, s16, 0x80
	s_addc_u32 s101, s17, 0
	global_load_lds_dwordx4 v16, s[100:101]
	s_add_i32 m0, s6, 0x2000
	s_add_u32 s6, s16, 0x100080
	s_addc_u32 s7, s17, 0
	s_add_i32 s16, s12, 0x1c000
	global_load_lds_dwordx4 v138, s[100:101]
	s_mov_b32 m0, s16
	ds_read_b128 v[206:209], v161 offset:56320
	global_load_lds_dwordx4 v16, s[6:7]
	s_add_i32 m0, s16, 0x2000
	ds_read_b128 v[202:205], v161 offset:55296
	global_load_lds_dwordx4 v138, s[6:7]
	s_mov_b32 m0, s68
	s_nop 0
	s_add_u32 vcc_lo, s40, 0x80
	s_addc_u32 vcc_hi, s41, 0
	global_load_lds_dwordx4 v142, vcc
	s_mov_b32 m0, s69
	ds_read_b128 v[198:201], v161 offset:54272
	global_load_lds_dwordx4 v140, vcc
	s_waitcnt vmcnt(8) lgkmcnt(0)
	s_nop 0
	s_barrier
	v_mfma_f32_16x16x32_bf16 v[62:65], v[130:133], v[178:181], v[62:65]
	v_mfma_f32_16x16x32_bf16 v[58:61], v[148:151], v[178:181], v[58:61]
	v_mfma_f32_16x16x32_bf16 v[46:49], v[130:133], v[186:189], v[46:49]
	v_mfma_f32_16x16x32_bf16 v[42:45], v[148:151], v[186:189], v[42:45]
	v_mfma_f32_16x16x32_bf16 v[30:33], v[130:133], v[194:197], v[30:33]
	v_mfma_f32_16x16x32_bf16 v[26:29], v[148:151], v[194:197], v[26:29]
	v_mfma_f32_16x16x32_bf16 v[12:15], v[130:133], v[202:205], v[12:15]
	v_mfma_f32_16x16x32_bf16 v[8:11], v[148:151], v[202:205], v[8:11]
	v_mfma_f32_16x16x32_bf16 v[62:65], v[134:137], v[182:185], v[62:65]
	v_mfma_f32_16x16x32_bf16 v[58:61], v[152:155], v[182:185], v[58:61]
	v_mfma_f32_16x16x32_bf16 v[46:49], v[134:137], v[190:193], v[46:49]
	v_mfma_f32_16x16x32_bf16 v[42:45], v[152:155], v[190:193], v[42:45]
	v_mfma_f32_16x16x32_bf16 v[30:33], v[134:137], v[198:201], v[30:33]
	v_mfma_f32_16x16x32_bf16 v[26:29], v[152:155], v[198:201], v[26:29]
	v_mfma_f32_16x16x32_bf16 v[12:15], v[134:137], v[206:209], v[12:15]
	v_mfma_f32_16x16x32_bf16 v[8:11], v[152:155], v[206:209], v[8:11]
	v_mfma_f32_16x16x32_bf16 v[54:57], v[162:165], v[178:181], v[54:57]
	v_mfma_f32_16x16x32_bf16 v[50:53], v[170:173], v[178:181], v[50:53]
	v_mfma_f32_16x16x32_bf16 v[38:41], v[162:165], v[186:189], v[38:41]
	v_mfma_f32_16x16x32_bf16 v[34:37], v[170:173], v[186:189], v[34:37]
	v_mfma_f32_16x16x32_bf16 v[22:25], v[162:165], v[194:197], v[22:25]
	v_mfma_f32_16x16x32_bf16 v[18:21], v[170:173], v[194:197], v[18:21]
	v_mfma_f32_16x16x32_bf16 v[4:7], v[162:165], v[202:205], v[4:7]
	v_mfma_f32_16x16x32_bf16 v[0:3], v[170:173], v[202:205], v[0:3]
	v_mfma_f32_16x16x32_bf16 v[54:57], v[166:169], v[182:185], v[54:57]
	v_mfma_f32_16x16x32_bf16 v[50:53], v[174:177], v[182:185], v[50:53]
	v_mfma_f32_16x16x32_bf16 v[38:41], v[166:169], v[190:193], v[38:41]
	v_mfma_f32_16x16x32_bf16 v[34:37], v[174:177], v[190:193], v[34:37]
	v_mfma_f32_16x16x32_bf16 v[22:25], v[166:169], v[198:201], v[22:25]
	v_mfma_f32_16x16x32_bf16 v[18:21], v[174:177], v[198:201], v[18:21]
	v_mfma_f32_16x16x32_bf16 v[4:7], v[166:169], v[206:209], v[4:7]
	v_mfma_f32_16x16x32_bf16 v[0:3], v[174:177], v[206:209], v[0:3]
	s_barrier
	s_add_i32 s90, s90, 2
	s_add_u32 s38, s38, 0x100
	s_addc_u32 s39, s39, 0
	s_add_u32 s0, s0, 0x100
	s_addc_u32 s1, s1, 0
	s_cmp_gt_u32 s90, 61
	s_cbranch_scc0 .LBB0_558
	s_and_b64 vcc, exec, s[18:19]
	s_cbranch_vccz .LBB0_561
	s_barrier

; #define PG8_STAGEA(bufoff, gbase, voff) PG8_STAGE_X(bufoff, gbase, voff, AUXA)
; #define PG8_STR(x) PG8_STR2(x)
;     ...
;         const bool has_next = S.next(ui + 1, nxt);
;         const char* nA = has_next ? (const char*)g.A + (size_t)nxt.pm * tstepA : cA; const char* nB = has_next ? (const char*)g.Bt + (size_t)nxt.pn * tstepB : cB;
;         int t0 = 0;
;         if constexpr (SP2 && GEMM_RELAX == 1) { if (ui > 0) {
;             const char* a1 = cA + kstepA; const char* a2 = cA + 2 * kstepA; const char* b2 = cB + 2 * kstepB; const char* a3 = a2 + kstepA; const char* b3 = b2 + kstepB;
;             PG8_LDB(B0, 0, 0); PG8_LDB(B1, 0, 1); PG8_SCHED; PG8_LDA(At, 0, 0); PG8_STAGEA(PG8_SA(1, 1), a1 + hstepA, voffA);
;             PG8_WAIT_V(24); PG8_WAIT_L(0); PG8_BAR; PG8_MMA(0, 0, At, B0); PG8_MMA(0, 1, At, B1); PG8_BAR; PG8_SCHED;
;             PG8_LDA(At, 0, 1); PG8_STAGEB(PG8_SB(0, 0), b2, voffB); PG8_STAGEB(PG8_SB(0, 1), b2 + hstepB, voffB); PG8_STAGEA(PG8_SA(0, 0), a2, voffA);
;             PG8_WAIT_V(24); PG8_WAIT_L(0); PG8_BAR; PG8_MMA(1, 0, At, B0); PG8_MMA(1, 1, At, B1); PG8_BAR; PG8_SCHED;
;             PG8_LDB(B0, 1, 0); PG8_LDB(B1, 1, 1); PG8_SCHED; PG8_LDA(At, 1, 0); PG8_STAGEA(PG8_SA(0, 1), a2 + hstepA, voffA);
;             PG8_WAIT_V(8); PG8_WAIT_L(0); PG8_BAR; PG8_MMA(0, 0, At, B0); PG8_MMA(0, 1, At, B1); PG8_BAR; PG8_SCHED;
;             PG8_LDA(At, 1, 1); PG8_STAGEB(PG8_SB(1, 0), b3, voffB); PG8_STAGEB(PG8_SB(1, 1), b3 + hstepB, voffB); PG8_STAGEA(PG8_SA(1, 0), a3, voffA);
;             PG8_WAIT_V(8); PG8_WAIT_L(0); PG8_BAR; PG8_MMA(1, 0, At, B0); PG8_MMA(1, 1, At, B1); PG8_BAR; PG8_SCHED;
;             t0 = 2; } }
;     ...
;         asm volatile(".p2align " PG8_STR(GEMM_LOOP_ALIGN) ::: "memory");
;     ...
;         for (int t = t0; t < nt; t += 2) {
;             const bool last = (t == nt - 2);
;             const char* a1 = cA + (size_t)(t + 1) * kstepA;
;             const char* a2 = last ? nA : cA + (size_t)(t + 2) * kstepA; const char* b2 = last ? nB : cB + (size_t)(t + 2) * kstepB;
;             const char* a3 = a2 + kstepA; const char* b3 = b2 + kstepB;
;             if (last && has_next) S.a_ready(nxt);
;             if constexpr (SP2) {
;             PG8_LDB(B0, 0, 0); PG8_LDB(B1, 0, 1); PG8_SCHED; PG8_LDA(At, 0, 0); PG8_STAGEA(PG8_SA(1, 1), a1 + hstepA, voffA);
;     ...
;             const int relax = __builtin_amdgcn_readfirstlane((t == 0 && ui > 0) ? 1 : 0);
.LBB0_711:
	s_ashr_i32 s25, s24, 31
	s_lshl_b64 s[0:1], s[24:25], 21
	s_add_u32 s26, s56, s0
	s_addc_u32 s27, s57, s1
	s_and_b64 s[0:1], s[10:11], exec
	s_cselect_b32 s0, s27, s13
	s_cselect_b32 s1, s26, s12
	s_ashr_i32 s23, s22, 31
	s_lshl_b64 s[6:7], s[22:23], 21
	s_add_u32 s36, s51, s6
	s_addc_u32 s37, s68, s7
	s_and_b64 s[6:7], s[10:11], exec
	s_cselect_b32 s23, s37, s43
	s_cselect_b32 s25, s36, s42
	s_add_u32 s40, s12, 0x100080
	s_addc_u32 s41, s13, 0
	s_add_u32 s12, s42, 0x100
	s_addc_u32 s13, s43, 0
	s_mov_b32 s39, -2
	s_add_u32 s6, s40, 0xfff00080
	s_addc_u32 s7, s41, -1
	s_add_i32 s95, 0, 0x10000
	s_cmp_eq_u32 s39, 60
	s_cselect_b32 s43, s0, s7
	s_cselect_b32 s42, s1, s6
	v_add_u32_e32 v144, s95, v146
	s_cselect_b32 s17, s23, s13
	s_cselect_b32 s16, s25, s12
	s_add_i32 vcc_lo, 0, 0x14000
	ds_read_b128 v[150:153], v144
	ds_read_b128 v[154:157], v144 offset:1024
	ds_read_b128 v[158:161], v144 offset:2048
	ds_read_b128 v[162:165], v144 offset:3072
	v_add_u32_e32 v144, vcc_lo, v146
	ds_read_b128 v[166:169], v144
	ds_read_b128 v[170:173], v144 offset:1024
	ds_read_b128 v[174:177], v144 offset:2048
	ds_read_b128 v[178:181], v144 offset:3072
	v_lshl_add_u64 v[144:145], s[40:41], 0, v[140:141]
	s_add_i32 m0, s69, 0xc000
	ds_read_b128 v[182:185], v148
	ds_read_b128 v[186:189], v148 offset:1024
	ds_read_b128 v[190:193], v148 offset:2048
	ds_read_b128 v[194:197], v148 offset:3072
	ds_read_b128 v[198:201], v148 offset:4096
	ds_read_b128 v[202:205], v148 offset:5120
	ds_read_b128 v[206:209], v148 offset:6144
	ds_read_b128 v[210:213], v148 offset:7168
	global_load_lds_dwordx4 v[144:145], off
	v_lshl_add_u64 v[144:145], s[40:41], 0, v[142:143]
	s_add_i32 m0, s69, 0xe000
	s_nop 0
	global_load_lds_dwordx4 v[144:145], off
	s_waitcnt vmcnt(8) lgkmcnt(0)
	s_barrier
	v_mfma_f32_16x16x32_bf16 v[126:129], v[150:153], v[182:185], 0
	v_mfma_f32_16x16x32_bf16 v[122:125], v[158:161], v[182:185], 0
	v_mfma_f32_16x16x32_bf16 v[110:113], v[150:153], v[190:193], 0
	v_mfma_f32_16x16x32_bf16 v[106:109], v[158:161], v[190:193], 0
	v_mfma_f32_16x16x32_bf16 v[94:97], v[150:153], v[198:201], 0
	v_mfma_f32_16x16x32_bf16 v[90:93], v[158:161], v[198:201], 0
	v_mfma_f32_16x16x32_bf16 v[78:81], v[150:153], v[206:209], 0
	v_mfma_f32_16x16x32_bf16 v[74:77], v[158:161], v[206:209], 0
	v_mfma_f32_16x16x32_bf16 v[126:129], v[154:157], v[186:189], v[126:129]
	v_mfma_f32_16x16x32_bf16 v[122:125], v[162:165], v[186:189], v[122:125]
	v_mfma_f32_16x16x32_bf16 v[110:113], v[154:157], v[194:197], v[110:113]
	v_mfma_f32_16x16x32_bf16 v[106:109], v[162:165], v[194:197], v[106:109]
	v_mfma_f32_16x16x32_bf16 v[94:97], v[154:157], v[202:205], v[94:97]
	v_mfma_f32_16x16x32_bf16 v[90:93], v[162:165], v[202:205], v[90:93]
	v_mfma_f32_16x16x32_bf16 v[78:81], v[154:157], v[210:213], v[78:81]
	v_mfma_f32_16x16x32_bf16 v[74:77], v[162:165], v[210:213], v[74:77]
	v_mfma_f32_16x16x32_bf16 v[118:121], v[166:169], v[182:185], 0
	v_mfma_f32_16x16x32_bf16 v[114:117], v[174:177], v[182:185], 0
	v_mfma_f32_16x16x32_bf16 v[102:105], v[166:169], v[190:193], 0
	v_mfma_f32_16x16x32_bf16 v[98:101], v[174:177], v[190:193], 0
	v_mfma_f32_16x16x32_bf16 v[86:89], v[166:169], v[198:201], 0
	v_mfma_f32_16x16x32_bf16 v[82:85], v[174:177], v[198:201], 0
	v_mfma_f32_16x16x32_bf16 v[70:73], v[166:169], v[206:209], 0
	v_mfma_f32_16x16x32_bf16 v[66:69], v[174:177], v[206:209], 0
	v_mfma_f32_16x16x32_bf16 v[118:121], v[170:173], v[186:189], v[118:121]
	v_mfma_f32_16x16x32_bf16 v[114:117], v[178:181], v[186:189], v[114:117]
	v_mfma_f32_16x16x32_bf16 v[102:105], v[170:173], v[194:197], v[102:105]
	v_mfma_f32_16x16x32_bf16 v[98:101], v[178:181], v[194:197], v[98:101]
	v_mfma_f32_16x16x32_bf16 v[86:89], v[170:173], v[202:205], v[86:89]
	v_mfma_f32_16x16x32_bf16 v[82:85], v[178:181], v[202:205], v[82:85]
	v_mfma_f32_16x16x32_bf16 v[70:73], v[170:173], v[210:213], v[70:73]
	v_mfma_f32_16x16x32_bf16 v[66:69], v[178:181], v[210:213], v[66:69]
	s_barrier
	s_add_i32 s6, s95, s50
	v_lshl_add_u64 v[144:145], s[16:17], 0, v[134:135]
	s_mov_b32 m0, s6
	ds_read_b128 v[182:185], v148 offset:16384
	ds_read_b128 v[186:189], v148 offset:17408
	ds_read_b128 v[190:193], v148 offset:18432
	ds_read_b128 v[194:197], v148 offset:19456
	ds_read_b128 v[198:201], v148 offset:20480
	ds_read_b128 v[202:205], v148 offset:21504
	ds_read_b128 v[206:209], v148 offset:22528
	ds_read_b128 v[210:213], v148 offset:23552
	global_load_lds_dwordx4 v[144:145], off
	s_add_i32 m0, s6, 0x2000
	s_add_u32 s6, s16, 0x100000
	v_lshl_add_u64 v[214:215], s[16:17], 0, v[130:131]
	s_addc_u32 s7, s17, 0
	s_add_i32 s95, vcc_lo, s50
	global_load_lds_dwordx4 v[214:215], off
	v_lshl_add_u64 v[216:217], s[6:7], 0, v[134:135]
	s_mov_b32 m0, s95
	v_lshl_add_u64 v[218:219], s[42:43], 0, v[132:133]
	global_load_lds_dwordx4 v[216:217], off
	v_lshl_add_u64 v[216:217], s[6:7], 0, v[130:131]
	s_add_i32 m0, s95, 0x2000
	s_nop 0
	global_load_lds_dwordx4 v[216:217], off
	v_lshl_add_u64 v[216:217], s[42:43], 0, v[136:137]
	s_mov_b32 m0, s69
	s_nop 0
	global_load_lds_dwordx4 v[216:217], off
	s_mov_b32 m0, s72
	s_nop 0
	global_load_lds_dwordx4 v[218:219], off
	s_waitcnt vmcnt(8) lgkmcnt(0)
	s_nop 0
	s_barrier
; #define PG8_STAGEA(bufoff, gbase, voff) PG8_STAGE_X(bufoff, gbase, voff, AUXA)
; #define PG8_STAGEB(bufoff, gbase, voff) PG8_STAGE_X(bufoff, gbase, voff, AUXB)
; #define PG8_LDA(dst, b, h) do { _Pragma("unroll") for (int m = 0; m < 4; ++m) _Pragma("unroll") for (int k = 0; k < 2; ++k) dst[m][k] = *(const PG8_LAS bf16x8*)(lds + PG8_SA(b, h) + aoff + m * 2048 + k * 1024); } while (0)
; #define PG8_LDB(dst, b, h) do { _Pragma("unroll") for (int n = 0; n < 2; ++n) _Pragma("unroll") for (int k = 0; k < 2; ++k) dst[n][k] = *(const PG8_LAS bf16x8*)(lds + PG8_SB(b, h) + boff + n * 2048 + k * 1024); } while (0)
; #define PG8_MMA(ai, bj, At, Bt) do { if (GEMM_PRIO_MODE == 0) __builtin_amdgcn_s_setprio(1); PG8_MMA_LOOPS \
;         acc[ai][bj][m][n] = __builtin_amdgcn_mfma_f32_16x16x32_bf16(Bt[n][k], At[m][k], acc[ai][bj][m][n], 0, 0, 0); if (GEMM_PRIO_MODE == 0) __builtin_amdgcn_s_setprio(0); } while (0)
; #define PG8_WAIT_V(n) asm volatile("s_waitcnt vmcnt(" #n ")" ::: "memory")
; #define PG8_WAIT_VR(n, nr, flag) asm volatile("s_cmp_eq_u32 %0, 0\n\ts_cbranch_scc1 .Lpg8s%=\n\ts_waitcnt vmcnt(" #nr ")\n\ts_branch .Lpg8d%=\n.Lpg8s%=:\n\ts_waitcnt vmcnt(" #n ")\n.Lpg8d%=:" :: "s"(flag) : "memory", "scc")
; #define PG8_WAIT_L(n) asm volatile("s_waitcnt lgkmcnt(" #n ")" ::: "memory")
; #define PG8_BAR __builtin_amdgcn_s_barrier()
; #define PG8_SCHED __builtin_amdgcn_sched_barrier(0)
;     ...
;             PG8_LDA(At, 0, 1); PG8_STAGEB(PG8_SB(0, 0), b2, voffB); PG8_STAGEB(PG8_SB(0, 1), b2 + hstepB, voffB); PG8_STAGEA(PG8_SA(0, 0), a2, voffA);
;     ...
;             PG8_WAIT_VR(8, 24, relax); PG8_WAIT_L(0); PG8_BAR; PG8_MMA(1, 0, At, B0); PG8_MMA(1, 1, At, B1); PG8_BAR; PG8_SCHED;
;     ...
;             PG8_WAIT_V(8); PG8_WAIT_L(0); PG8_BAR; PG8_MMA(1, 0, At, B0); PG8_MMA(1, 1, At, B1); PG8_BAR; PG8_SCHED;
;     ...
;             PG8_LDB(B0, 1, 0); PG8_LDB(B1, 1, 1); PG8_SCHED; PG8_LDA(At, 1, 0); PG8_STAGEA(PG8_SA(0, 1), a2 + hstepA, voffA);
;             PG8_WAIT_V(8); PG8_WAIT_L(0); PG8_BAR; PG8_MMA(0, 0, At, B0); PG8_MMA(0, 1, At, B1); PG8_BAR; PG8_SCHED;
;             PG8_LDA(At, 1, 1); PG8_STAGEB(PG8_SB(1, 0), b3, voffB); PG8_STAGEB(PG8_SB(1, 1), b3 + hstepB, voffB); PG8_STAGEA(PG8_SA(1, 0), a3, voffA);
;             PG8_WAIT_V(8); PG8_WAIT_L(0); PG8_BAR; PG8_MMA(1, 0, At, B0); PG8_MMA(1, 1, At, B1); PG8_BAR; PG8_SCHED;
	v_mfma_f32_16x16x32_bf16 v[62:65], v[150:153], v[182:185], 0
	v_mfma_f32_16x16x32_bf16 v[58:61], v[158:161], v[182:185], 0
	v_mfma_f32_16x16x32_bf16 v[46:49], v[150:153], v[190:193], 0
	v_mfma_f32_16x16x32_bf16 v[42:45], v[158:161], v[190:193], 0
	v_mfma_f32_16x16x32_bf16 v[30:33], v[150:153], v[198:201], 0
	v_mfma_f32_16x16x32_bf16 v[26:29], v[158:161], v[198:201], 0
	v_mfma_f32_16x16x32_bf16 v[12:15], v[150:153], v[206:209], 0
	v_mfma_f32_16x16x32_bf16 v[8:11], v[158:161], v[206:209], 0
	v_mfma_f32_16x16x32_bf16 v[62:65], v[154:157], v[186:189], v[62:65]
	v_mfma_f32_16x16x32_bf16 v[58:61], v[162:165], v[186:189], v[58:61]
	v_mfma_f32_16x16x32_bf16 v[46:49], v[154:157], v[194:197], v[46:49]
	v_mfma_f32_16x16x32_bf16 v[42:45], v[162:165], v[194:197], v[42:45]
	v_mfma_f32_16x16x32_bf16 v[30:33], v[154:157], v[202:205], v[30:33]
	v_mfma_f32_16x16x32_bf16 v[26:29], v[162:165], v[202:205], v[26:29]
	v_mfma_f32_16x16x32_bf16 v[12:15], v[154:157], v[210:213], v[12:15]
	v_mfma_f32_16x16x32_bf16 v[8:11], v[162:165], v[210:213], v[8:11]
	v_mfma_f32_16x16x32_bf16 v[54:57], v[166:169], v[182:185], 0
	v_mfma_f32_16x16x32_bf16 v[50:53], v[174:177], v[182:185], 0
	v_mfma_f32_16x16x32_bf16 v[38:41], v[166:169], v[190:193], 0
	v_mfma_f32_16x16x32_bf16 v[34:37], v[174:177], v[190:193], 0
	v_mfma_f32_16x16x32_bf16 v[22:25], v[166:169], v[198:201], 0
	v_mfma_f32_16x16x32_bf16 v[18:21], v[174:177], v[198:201], 0
	v_mfma_f32_16x16x32_bf16 v[4:7], v[166:169], v[206:209], 0
	v_mfma_f32_16x16x32_bf16 v[0:3], v[174:177], v[206:209], 0
	v_mfma_f32_16x16x32_bf16 v[54:57], v[170:173], v[186:189], v[54:57]
	v_mfma_f32_16x16x32_bf16 v[50:53], v[178:181], v[186:189], v[50:53]
	v_mfma_f32_16x16x32_bf16 v[38:41], v[170:173], v[194:197], v[38:41]
	v_mfma_f32_16x16x32_bf16 v[34:37], v[178:181], v[194:197], v[34:37]
	v_mfma_f32_16x16x32_bf16 v[22:25], v[170:173], v[202:205], v[22:25]
	v_mfma_f32_16x16x32_bf16 v[18:21], v[178:181], v[202:205], v[18:21]
	v_mfma_f32_16x16x32_bf16 v[4:7], v[170:173], v[210:213], v[4:7]
	v_mfma_f32_16x16x32_bf16 v[0:3], v[178:181], v[210:213], v[0:3]
	s_barrier
	s_add_i32 s95, 0, 0x18000
	v_add_u32_e32 v149, s95, v146
	s_add_i32 vcc_lo, 0, 0x1c000
	ds_read_b128 v[150:153], v149
	ds_read_b128 v[154:157], v149 offset:1024
	ds_read_b128 v[158:161], v149 offset:2048
	ds_read_b128 v[162:165], v149 offset:3072
	v_add_u32_e32 v149, vcc_lo, v146
	ds_read_b128 v[166:169], v149
	ds_read_b128 v[170:173], v149 offset:1024
	ds_read_b128 v[174:177], v149 offset:2048
	ds_read_b128 v[178:181], v149 offset:3072
	s_add_u32 s6, s42, 0x100000
	s_addc_u32 s7, s43, 0
	s_mov_b32 m0, s73
	v_lshl_add_u64 v[220:221], s[6:7], 0, v[136:137]
	ds_read_b128 v[182:185], v148 offset:32768
	ds_read_b128 v[186:189], v148 offset:33792
	ds_read_b128 v[190:193], v148 offset:34816
	ds_read_b128 v[194:197], v148 offset:35840
	ds_read_b128 v[198:201], v148 offset:36864
	ds_read_b128 v[202:205], v148 offset:37888
	ds_read_b128 v[206:209], v148 offset:38912
	ds_read_b128 v[210:213], v148 offset:39936
	global_load_lds_dwordx4 v[220:221], off
	v_lshl_add_u64 v[220:221], s[6:7], 0, v[132:133]
	s_mov_b32 m0, s82
	s_nop 0
	global_load_lds_dwordx4 v[220:221], off
	s_waitcnt vmcnt(8) lgkmcnt(0)
	s_nop 0
	s_barrier
	v_mfma_f32_16x16x32_bf16 v[126:129], v[150:153], v[182:185], v[126:129]
	v_mfma_f32_16x16x32_bf16 v[122:125], v[158:161], v[182:185], v[122:125]
	v_mfma_f32_16x16x32_bf16 v[110:113], v[150:153], v[190:193], v[110:113]
	v_mfma_f32_16x16x32_bf16 v[106:109], v[158:161], v[190:193], v[106:109]
	v_mfma_f32_16x16x32_bf16 v[94:97], v[150:153], v[198:201], v[94:97]
	v_mfma_f32_16x16x32_bf16 v[90:93], v[158:161], v[198:201], v[90:93]
	v_mfma_f32_16x16x32_bf16 v[78:81], v[150:153], v[206:209], v[78:81]
	v_mfma_f32_16x16x32_bf16 v[74:77], v[158:161], v[206:209], v[74:77]
	v_mfma_f32_16x16x32_bf16 v[126:129], v[154:157], v[186:189], v[126:129]
	v_mfma_f32_16x16x32_bf16 v[122:125], v[162:165], v[186:189], v[122:125]
	v_mfma_f32_16x16x32_bf16 v[110:113], v[154:157], v[194:197], v[110:113]
	v_mfma_f32_16x16x32_bf16 v[106:109], v[162:165], v[194:197], v[106:109]
	v_mfma_f32_16x16x32_bf16 v[94:97], v[154:157], v[202:205], v[94:97]
	v_mfma_f32_16x16x32_bf16 v[90:93], v[162:165], v[202:205], v[90:93]
	v_mfma_f32_16x16x32_bf16 v[78:81], v[154:157], v[210:213], v[78:81]
	v_mfma_f32_16x16x32_bf16 v[74:77], v[162:165], v[210:213], v[74:77]
	v_mfma_f32_16x16x32_bf16 v[118:121], v[166:169], v[182:185], v[118:121]
	v_mfma_f32_16x16x32_bf16 v[114:117], v[174:177], v[182:185], v[114:117]
	v_mfma_f32_16x16x32_bf16 v[102:105], v[166:169], v[190:193], v[102:105]
	v_mfma_f32_16x16x32_bf16 v[98:101], v[174:177], v[190:193], v[98:101]
	v_mfma_f32_16x16x32_bf16 v[86:89], v[166:169], v[198:201], v[86:89]
	v_mfma_f32_16x16x32_bf16 v[82:85], v[174:177], v[198:201], v[82:85]
	v_mfma_f32_16x16x32_bf16 v[70:73], v[166:169], v[206:209], v[70:73]
	v_mfma_f32_16x16x32_bf16 v[66:69], v[174:177], v[206:209], v[66:69]
	v_mfma_f32_16x16x32_bf16 v[118:121], v[170:173], v[186:189], v[118:121]
	v_mfma_f32_16x16x32_bf16 v[114:117], v[178:181], v[186:189], v[114:117]
	v_mfma_f32_16x16x32_bf16 v[102:105], v[170:173], v[194:197], v[102:105]
	v_mfma_f32_16x16x32_bf16 v[98:101], v[178:181], v[194:197], v[98:101]
	v_mfma_f32_16x16x32_bf16 v[86:89], v[170:173], v[202:205], v[86:89]
	v_mfma_f32_16x16x32_bf16 v[82:85], v[178:181], v[202:205], v[82:85]
	v_mfma_f32_16x16x32_bf16 v[70:73], v[170:173], v[210:213], v[70:73]
	v_mfma_f32_16x16x32_bf16 v[66:69], v[178:181], v[210:213], v[66:69]
	s_barrier
; #define PG8_STAGEA(bufoff, gbase, voff) PG8_STAGE_X(bufoff, gbase, voff, AUXA)
; #define PG8_STAGEB(bufoff, gbase, voff) PG8_STAGE_X(bufoff, gbase, voff, AUXB)
; #define PG8_LDA(dst, b, h) do { _Pragma("unroll") for (int m = 0; m < 4; ++m) _Pragma("unroll") for (int k = 0; k < 2; ++k) dst[m][k] = *(const PG8_LAS bf16x8*)(lds + PG8_SA(b, h) + aoff + m * 2048 + k * 1024); } while (0)
; #define PG8_WAIT_V(n) asm volatile("s_waitcnt vmcnt(" #n ")" ::: "memory")
; #define PG8_WAIT_L(n) asm volatile("s_waitcnt lgkmcnt(" #n ")" ::: "memory")
;     ...
;         for (int t = t0; t < nt; t += 2) {
;             const bool last = (t == nt - 2);
;             const char* a1 = cA + (size_t)(t + 1) * kstepA;
;             const char* a2 = last ? nA : cA + (size_t)(t + 2) * kstepA; const char* b2 = last ? nB : cB + (size_t)(t + 2) * kstepB;
;             const char* a3 = a2 + kstepA; const char* b3 = b2 + kstepB;
;             if (last && has_next) S.a_ready(nxt);
;             if constexpr (SP2) {
;             PG8_LDB(B0, 0, 0); PG8_LDB(B1, 0, 1); PG8_SCHED; PG8_LDA(At, 0, 0); PG8_STAGEA(PG8_SA(1, 1), a1 + hstepA, voffA);
;     ...
;             const int relax = __builtin_amdgcn_readfirstlane((t == 0 && ui > 0) ? 1 : 0);
;             PG8_WAIT_VR(8, 24, relax); PG8_WAIT_L(0); PG8_BAR; PG8_MMA(0, 0, At, B0); PG8_MMA(0, 1, At, B1); PG8_BAR; PG8_SCHED;
;     ...
;             PG8_WAIT_V(8); PG8_WAIT_L(0); PG8_BAR; PG8_MMA(0, 0, At, B0); PG8_MMA(0, 1, At, B1); PG8_BAR; PG8_SCHED;
;     ...
;             PG8_LDA(At, 0, 1); PG8_STAGEB(PG8_SB(0, 0), b2, voffB); PG8_STAGEB(PG8_SB(0, 1), b2 + hstepB, voffB); PG8_STAGEA(PG8_SA(0, 0), a2, voffA);
;     ...
;             PG8_WAIT_VR(8, 24, relax); PG8_WAIT_L(0); PG8_BAR; PG8_MMA(1, 0, At, B0); PG8_MMA(1, 1, At, B1); PG8_BAR; PG8_SCHED;
;     ...
;             PG8_WAIT_V(8); PG8_WAIT_L(0); PG8_BAR; PG8_MMA(1, 0, At, B0); PG8_MMA(1, 1, At, B1); PG8_BAR; PG8_SCHED;
;     ...
;             PG8_LDB(B0, 1, 0); PG8_LDB(B1, 1, 1); PG8_SCHED; PG8_LDA(At, 1, 0); PG8_STAGEA(PG8_SA(0, 1), a2 + hstepA, voffA);
;             PG8_WAIT_V(8); PG8_WAIT_L(0); PG8_BAR; PG8_MMA(0, 0, At, B0); PG8_MMA(0, 1, At, B1); PG8_BAR; PG8_SCHED;
;             PG8_LDA(At, 1, 1); PG8_STAGEB(PG8_SB(1, 0), b3, voffB); PG8_STAGEB(PG8_SB(1, 1), b3 + hstepB, voffB); PG8_STAGEA(PG8_SA(1, 0), a3, voffA);
;             PG8_WAIT_V(8); PG8_WAIT_L(0); PG8_BAR; PG8_MMA(1, 0, At, B0); PG8_MMA(1, 1, At, B1); PG8_BAR; PG8_SCHED;
	s_add_i32 s6, s95, s50
	v_lshl_add_u64 v[144:145], v[144:145], 0, s[86:87]
	s_mov_b32 m0, s6
	ds_read_b128 v[182:185], v148 offset:49152
	ds_read_b128 v[186:189], v148 offset:50176
	ds_read_b128 v[190:193], v148 offset:51200
	ds_read_b128 v[194:197], v148 offset:52224
	ds_read_b128 v[198:201], v148 offset:53248
	ds_read_b128 v[202:205], v148 offset:54272
	ds_read_b128 v[206:209], v148 offset:55296
	ds_read_b128 v[210:213], v148 offset:56320
	global_load_lds_dwordx4 v[144:145], off
	s_add_i32 m0, s6, 0x2000
	s_add_u32 s6, s16, 0x100080
	v_lshl_add_u64 v[144:145], v[214:215], 0, s[86:87]
	s_addc_u32 s7, s17, 0
	s_add_i32 s16, vcc_lo, s50
	global_load_lds_dwordx4 v[144:145], off
	v_lshl_add_u64 v[144:145], s[6:7], 0, v[134:135]
	s_mov_b32 m0, s16
	s_nop 0
	global_load_lds_dwordx4 v[144:145], off
	v_lshl_add_u64 v[144:145], s[6:7], 0, v[130:131]
	s_add_i32 m0, s16, 0x2000
	s_nop 0
	global_load_lds_dwordx4 v[144:145], off
	v_lshl_add_u64 v[144:145], v[216:217], 0, s[86:87]
	s_mov_b32 m0, s83
	s_nop 0
	global_load_lds_dwordx4 v[144:145], off
	v_lshl_add_u64 v[144:145], v[218:219], 0, s[86:87]
	s_mov_b32 m0, s90
	s_nop 0
	global_load_lds_dwordx4 v[144:145], off
	s_waitcnt vmcnt(8) lgkmcnt(0)
	s_barrier
	v_mfma_f32_16x16x32_bf16 v[62:65], v[150:153], v[182:185], v[62:65]
	v_mfma_f32_16x16x32_bf16 v[58:61], v[158:161], v[182:185], v[58:61]
	v_mfma_f32_16x16x32_bf16 v[46:49], v[150:153], v[190:193], v[46:49]
	v_mfma_f32_16x16x32_bf16 v[42:45], v[158:161], v[190:193], v[42:45]
	v_mfma_f32_16x16x32_bf16 v[30:33], v[150:153], v[198:201], v[30:33]
	v_mfma_f32_16x16x32_bf16 v[26:29], v[158:161], v[198:201], v[26:29]
	v_mfma_f32_16x16x32_bf16 v[12:15], v[150:153], v[206:209], v[12:15]
	v_mfma_f32_16x16x32_bf16 v[8:11], v[158:161], v[206:209], v[8:11]
	v_mfma_f32_16x16x32_bf16 v[62:65], v[154:157], v[186:189], v[62:65]
	v_mfma_f32_16x16x32_bf16 v[58:61], v[162:165], v[186:189], v[58:61]
	v_mfma_f32_16x16x32_bf16 v[46:49], v[154:157], v[194:197], v[46:49]
	v_mfma_f32_16x16x32_bf16 v[42:45], v[162:165], v[194:197], v[42:45]
	v_mfma_f32_16x16x32_bf16 v[30:33], v[154:157], v[202:205], v[30:33]
	v_mfma_f32_16x16x32_bf16 v[26:29], v[162:165], v[202:205], v[26:29]
	v_mfma_f32_16x16x32_bf16 v[12:15], v[154:157], v[210:213], v[12:15]
	v_mfma_f32_16x16x32_bf16 v[8:11], v[162:165], v[210:213], v[8:11]
	v_mfma_f32_16x16x32_bf16 v[54:57], v[166:169], v[182:185], v[54:57]
	v_mfma_f32_16x16x32_bf16 v[50:53], v[174:177], v[182:185], v[50:53]
	v_mfma_f32_16x16x32_bf16 v[38:41], v[166:169], v[190:193], v[38:41]
	v_mfma_f32_16x16x32_bf16 v[34:37], v[174:177], v[190:193], v[34:37]
	v_mfma_f32_16x16x32_bf16 v[22:25], v[166:169], v[198:201], v[22:25]
	v_mfma_f32_16x16x32_bf16 v[18:21], v[174:177], v[198:201], v[18:21]
	v_mfma_f32_16x16x32_bf16 v[4:7], v[166:169], v[206:209], v[4:7]
	v_mfma_f32_16x16x32_bf16 v[0:3], v[174:177], v[206:209], v[0:3]
	v_mfma_f32_16x16x32_bf16 v[54:57], v[170:173], v[186:189], v[54:57]
	v_mfma_f32_16x16x32_bf16 v[50:53], v[178:181], v[186:189], v[50:53]
	v_mfma_f32_16x16x32_bf16 v[38:41], v[170:173], v[194:197], v[38:41]
	v_mfma_f32_16x16x32_bf16 v[34:37], v[178:181], v[194:197], v[34:37]
	v_mfma_f32_16x16x32_bf16 v[22:25], v[170:173], v[202:205], v[22:25]
	v_mfma_f32_16x16x32_bf16 v[18:21], v[178:181], v[202:205], v[18:21]
	v_mfma_f32_16x16x32_bf16 v[4:7], v[170:173], v[210:213], v[4:7]
	v_mfma_f32_16x16x32_bf16 v[0:3], v[178:181], v[210:213], v[0:3]
	s_barrier
	s_add_i32 s39, s39, 2
	s_add_u32 s40, s40, 0x100
	s_addc_u32 s41, s41, 0
	s_add_u32 s12, s12, 0x100
	s_addc_u32 s13, s13, 0
	v_add_u32_e32 v222, 0x10000, v146
.LBB0_712:
	s_add_u32 s6, s40, 0xfff00080
	s_addc_u32 s7, s41, -1
	s_cmp_eq_u32 s39, 60
	s_cselect_b32 s43, s0, s7
	s_cselect_b32 s42, s1, s6
	s_cselect_b32 s17, s23, s13
	s_cselect_b32 s16, s25, s12
	ds_read_b128 v[150:153], v222
	ds_read_b128 v[154:157], v222 offset:1024
	ds_read_b128 v[158:161], v222 offset:2048
	ds_read_b128 v[162:165], v222 offset:3072
	ds_read_b128 v[166:169], v222 offset:16384
	ds_read_b128 v[170:173], v222 offset:17408
	ds_read_b128 v[174:177], v222 offset:18432
	ds_read_b128 v[178:181], v222 offset:19456
	s_add_i32 m0, s69, 0xc000
	ds_read_b128 v[182:185], v148
	ds_read_b128 v[186:189], v148 offset:1024
	ds_read_b128 v[190:193], v148 offset:2048
	ds_read_b128 v[194:197], v148 offset:3072
	ds_read_b128 v[198:201], v148 offset:4096
	ds_read_b128 v[202:205], v148 offset:5120
	ds_read_b128 v[206:209], v148 offset:6144
	global_load_lds_dwordx4 v140, s[40:41]
	s_add_i32 m0, s69, 0xe000
	ds_read_b128 v[210:213], v148 offset:7168
	global_load_lds_dwordx4 v142, s[40:41]
	s_waitcnt vmcnt(8) lgkmcnt(0)
	s_barrier
; #define PG8_STAGEA(bufoff, gbase, voff) PG8_STAGE_X(bufoff, gbase, voff, AUXA)
; #define PG8_STAGEB(bufoff, gbase, voff) PG8_STAGE_X(bufoff, gbase, voff, AUXB)
; #define PG8_LDA(dst, b, h) do { _Pragma("unroll") for (int m = 0; m < 4; ++m) _Pragma("unroll") for (int k = 0; k < 2; ++k) dst[m][k] = *(const PG8_LAS bf16x8*)(lds + PG8_SA(b, h) + aoff + m * 2048 + k * 1024); } while (0)
; #define PG8_LDB(dst, b, h) do { _Pragma("unroll") for (int n = 0; n < 2; ++n) _Pragma("unroll") for (int k = 0; k < 2; ++k) dst[n][k] = *(const PG8_LAS bf16x8*)(lds + PG8_SB(b, h) + boff + n * 2048 + k * 1024); } while (0)
; #define PG8_MMA(ai, bj, At, Bt) do { if (GEMM_PRIO_MODE == 0) __builtin_amdgcn_s_setprio(1); PG8_MMA_LOOPS \
;         acc[ai][bj][m][n] = __builtin_amdgcn_mfma_f32_16x16x32_bf16(Bt[n][k], At[m][k], acc[ai][bj][m][n], 0, 0, 0); if (GEMM_PRIO_MODE == 0) __builtin_amdgcn_s_setprio(0); } while (0)
; #define PG8_WAIT_V(n) asm volatile("s_waitcnt vmcnt(" #n ")" ::: "memory")
;     ...
;             PG8_LDB(B0, 0, 0); PG8_LDB(B1, 0, 1); PG8_SCHED; PG8_LDA(At, 0, 0); PG8_STAGEA(PG8_SA(1, 1), a1 + hstepA, voffA);
;     ...
;             const int relax = __builtin_amdgcn_readfirstlane((t == 0 && ui > 0) ? 1 : 0);
;             PG8_WAIT_VR(8, 24, relax); PG8_WAIT_L(0); PG8_BAR; PG8_MMA(0, 0, At, B0); PG8_MMA(0, 1, At, B1); PG8_BAR; PG8_SCHED;
;     ...
;             PG8_WAIT_V(8); PG8_WAIT_L(0); PG8_BAR; PG8_MMA(0, 0, At, B0); PG8_MMA(0, 1, At, B1); PG8_BAR; PG8_SCHED;
;     ...
;             PG8_LDA(At, 0, 1); PG8_STAGEB(PG8_SB(0, 0), b2, voffB); PG8_STAGEB(PG8_SB(0, 1), b2 + hstepB, voffB); PG8_STAGEA(PG8_SA(0, 0), a2, voffA);
;     ...
;             PG8_WAIT_VR(8, 24, relax); PG8_WAIT_L(0); PG8_BAR; PG8_MMA(1, 0, At, B0); PG8_MMA(1, 1, At, B1); PG8_BAR; PG8_SCHED;
;     ...
;             PG8_WAIT_V(8); PG8_WAIT_L(0); PG8_BAR; PG8_MMA(1, 0, At, B0); PG8_MMA(1, 1, At, B1); PG8_BAR; PG8_SCHED;
;     ...
;             PG8_LDB(B0, 1, 0); PG8_LDB(B1, 1, 1); PG8_SCHED; PG8_LDA(At, 1, 0); PG8_STAGEA(PG8_SA(0, 1), a2 + hstepA, voffA);
;             PG8_WAIT_V(8); PG8_WAIT_L(0); PG8_BAR; PG8_MMA(0, 0, At, B0); PG8_MMA(0, 1, At, B1); PG8_BAR; PG8_SCHED;
;             PG8_LDA(At, 1, 1); PG8_STAGEB(PG8_SB(1, 0), b3, voffB); PG8_STAGEB(PG8_SB(1, 1), b3 + hstepB, voffB); PG8_STAGEA(PG8_SA(1, 0), a3, voffA);
;             PG8_WAIT_V(8); PG8_WAIT_L(0); PG8_BAR; PG8_MMA(1, 0, At, B0); PG8_MMA(1, 1, At, B1); PG8_BAR; PG8_SCHED;
	v_mfma_f32_16x16x32_bf16 v[126:129], v[150:153], v[182:185], v[126:129]
	v_mfma_f32_16x16x32_bf16 v[122:125], v[158:161], v[182:185], v[122:125]
	v_mfma_f32_16x16x32_bf16 v[110:113], v[150:153], v[190:193], v[110:113]
	v_mfma_f32_16x16x32_bf16 v[106:109], v[158:161], v[190:193], v[106:109]
	v_mfma_f32_16x16x32_bf16 v[94:97], v[150:153], v[198:201], v[94:97]
	v_mfma_f32_16x16x32_bf16 v[90:93], v[158:161], v[198:201], v[90:93]
	v_mfma_f32_16x16x32_bf16 v[78:81], v[150:153], v[206:209], v[78:81]
	v_mfma_f32_16x16x32_bf16 v[74:77], v[158:161], v[206:209], v[74:77]
	v_mfma_f32_16x16x32_bf16 v[126:129], v[154:157], v[186:189], v[126:129]
	v_mfma_f32_16x16x32_bf16 v[122:125], v[162:165], v[186:189], v[122:125]
	v_mfma_f32_16x16x32_bf16 v[110:113], v[154:157], v[194:197], v[110:113]
	v_mfma_f32_16x16x32_bf16 v[106:109], v[162:165], v[194:197], v[106:109]
	v_mfma_f32_16x16x32_bf16 v[94:97], v[154:157], v[202:205], v[94:97]
	v_mfma_f32_16x16x32_bf16 v[90:93], v[162:165], v[202:205], v[90:93]
	v_mfma_f32_16x16x32_bf16 v[78:81], v[154:157], v[210:213], v[78:81]
	v_mfma_f32_16x16x32_bf16 v[74:77], v[162:165], v[210:213], v[74:77]
	v_mfma_f32_16x16x32_bf16 v[118:121], v[166:169], v[182:185], v[118:121]
	v_mfma_f32_16x16x32_bf16 v[114:117], v[174:177], v[182:185], v[114:117]
	v_mfma_f32_16x16x32_bf16 v[102:105], v[166:169], v[190:193], v[102:105]
	v_mfma_f32_16x16x32_bf16 v[98:101], v[174:177], v[190:193], v[98:101]
	v_mfma_f32_16x16x32_bf16 v[86:89], v[166:169], v[198:201], v[86:89]
	v_mfma_f32_16x16x32_bf16 v[82:85], v[174:177], v[198:201], v[82:85]
	v_mfma_f32_16x16x32_bf16 v[70:73], v[166:169], v[206:209], v[70:73]
	v_mfma_f32_16x16x32_bf16 v[66:69], v[174:177], v[206:209], v[66:69]
	v_mfma_f32_16x16x32_bf16 v[118:121], v[170:173], v[186:189], v[118:121]
	v_mfma_f32_16x16x32_bf16 v[114:117], v[178:181], v[186:189], v[114:117]
	v_mfma_f32_16x16x32_bf16 v[102:105], v[170:173], v[194:197], v[102:105]
	v_mfma_f32_16x16x32_bf16 v[98:101], v[178:181], v[194:197], v[98:101]
	v_mfma_f32_16x16x32_bf16 v[86:89], v[170:173], v[202:205], v[86:89]
	v_mfma_f32_16x16x32_bf16 v[82:85], v[178:181], v[202:205], v[82:85]
	v_mfma_f32_16x16x32_bf16 v[70:73], v[170:173], v[210:213], v[70:73]
	v_mfma_f32_16x16x32_bf16 v[66:69], v[178:181], v[210:213], v[66:69]
	s_barrier
	s_add_i32 s6, s50, 0x10000
	s_mov_b32 m0, s6
	ds_read_b128 v[182:185], v148 offset:16384
	ds_read_b128 v[186:189], v148 offset:17408
	ds_read_b128 v[190:193], v148 offset:18432
	ds_read_b128 v[194:197], v148 offset:19456
	global_load_lds_dwordx4 v134, s[16:17]
	s_add_i32 m0, s6, 0x2000
	s_add_u32 s6, s16, 0x100000
	s_addc_u32 s7, s17, 0
	s_add_i32 s95, s50, 0x14000
	global_load_lds_dwordx4 v130, s[16:17]
	s_mov_b32 m0, s95
	ds_read_b128 v[210:213], v148 offset:23552
	global_load_lds_dwordx4 v134, s[6:7]
	s_add_i32 m0, s95, 0x2000
	ds_read_b128 v[206:209], v148 offset:22528
	global_load_lds_dwordx4 v130, s[6:7]
	s_mov_b32 m0, s69
	ds_read_b128 v[202:205], v148 offset:21504
	global_load_lds_dwordx4 v136, s[42:43]
	s_mov_b32 m0, s72
	ds_read_b128 v[198:201], v148 offset:20480
	global_load_lds_dwordx4 v132, s[42:43]
	s_waitcnt vmcnt(8) lgkmcnt(0)
	s_barrier
	v_mfma_f32_16x16x32_bf16 v[62:65], v[150:153], v[182:185], v[62:65]
	v_mfma_f32_16x16x32_bf16 v[58:61], v[158:161], v[182:185], v[58:61]
	v_mfma_f32_16x16x32_bf16 v[46:49], v[150:153], v[190:193], v[46:49]
	v_mfma_f32_16x16x32_bf16 v[42:45], v[158:161], v[190:193], v[42:45]
	v_mfma_f32_16x16x32_bf16 v[30:33], v[150:153], v[198:201], v[30:33]
	v_mfma_f32_16x16x32_bf16 v[26:29], v[158:161], v[198:201], v[26:29]
	v_mfma_f32_16x16x32_bf16 v[12:15], v[150:153], v[206:209], v[12:15]
	v_mfma_f32_16x16x32_bf16 v[8:11], v[158:161], v[206:209], v[8:11]
	v_mfma_f32_16x16x32_bf16 v[62:65], v[154:157], v[186:189], v[62:65]
	v_mfma_f32_16x16x32_bf16 v[58:61], v[162:165], v[186:189], v[58:61]
	v_mfma_f32_16x16x32_bf16 v[46:49], v[154:157], v[194:197], v[46:49]
	v_mfma_f32_16x16x32_bf16 v[42:45], v[162:165], v[194:197], v[42:45]
	v_mfma_f32_16x16x32_bf16 v[30:33], v[154:157], v[202:205], v[30:33]
	v_mfma_f32_16x16x32_bf16 v[26:29], v[162:165], v[202:205], v[26:29]
	v_mfma_f32_16x16x32_bf16 v[12:15], v[154:157], v[210:213], v[12:15]
	v_mfma_f32_16x16x32_bf16 v[8:11], v[162:165], v[210:213], v[8:11]
	v_mfma_f32_16x16x32_bf16 v[54:57], v[166:169], v[182:185], v[54:57]
	v_mfma_f32_16x16x32_bf16 v[50:53], v[174:177], v[182:185], v[50:53]
	v_mfma_f32_16x16x32_bf16 v[38:41], v[166:169], v[190:193], v[38:41]
	v_mfma_f32_16x16x32_bf16 v[34:37], v[174:177], v[190:193], v[34:37]
	v_mfma_f32_16x16x32_bf16 v[22:25], v[166:169], v[198:201], v[22:25]
	v_mfma_f32_16x16x32_bf16 v[18:21], v[174:177], v[198:201], v[18:21]
	v_mfma_f32_16x16x32_bf16 v[4:7], v[166:169], v[206:209], v[4:7]
	v_mfma_f32_16x16x32_bf16 v[0:3], v[174:177], v[206:209], v[0:3]
	v_mfma_f32_16x16x32_bf16 v[54:57], v[170:173], v[186:189], v[54:57]
	v_mfma_f32_16x16x32_bf16 v[50:53], v[178:181], v[186:189], v[50:53]
	v_mfma_f32_16x16x32_bf16 v[38:41], v[170:173], v[194:197], v[38:41]
	v_mfma_f32_16x16x32_bf16 v[34:37], v[178:181], v[194:197], v[34:37]
	v_mfma_f32_16x16x32_bf16 v[22:25], v[170:173], v[202:205], v[22:25]
	v_mfma_f32_16x16x32_bf16 v[18:21], v[178:181], v[202:205], v[18:21]
	v_mfma_f32_16x16x32_bf16 v[4:7], v[170:173], v[210:213], v[4:7]
	v_mfma_f32_16x16x32_bf16 v[0:3], v[178:181], v[210:213], v[0:3]
	s_barrier
; #define PG8_STAGEA(bufoff, gbase, voff) PG8_STAGE_X(bufoff, gbase, voff, AUXA)
; #define PG8_STAGEB(bufoff, gbase, voff) PG8_STAGE_X(bufoff, gbase, voff, AUXB)
; #define PG8_LDA(dst, b, h) do { _Pragma("unroll") for (int m = 0; m < 4; ++m) _Pragma("unroll") for (int k = 0; k < 2; ++k) dst[m][k] = *(const PG8_LAS bf16x8*)(lds + PG8_SA(b, h) + aoff + m * 2048 + k * 1024); } while (0)
; #define PG8_LDB(dst, b, h) do { _Pragma("unroll") for (int n = 0; n < 2; ++n) _Pragma("unroll") for (int k = 0; k < 2; ++k) dst[n][k] = *(const PG8_LAS bf16x8*)(lds + PG8_SB(b, h) + boff + n * 2048 + k * 1024); } while (0)
; #define PG8_MMA(ai, bj, At, Bt) do { if (GEMM_PRIO_MODE == 0) __builtin_amdgcn_s_setprio(1); PG8_MMA_LOOPS \
;         acc[ai][bj][m][n] = __builtin_amdgcn_mfma_f32_16x16x32_bf16(Bt[n][k], At[m][k], acc[ai][bj][m][n], 0, 0, 0); if (GEMM_PRIO_MODE == 0) __builtin_amdgcn_s_setprio(0); } while (0)
; #define PG8_WAIT_V(n) asm volatile("s_waitcnt vmcnt(" #n ")" ::: "memory")
;     ...
;             PG8_LDB(B0, 0, 0); PG8_LDB(B1, 0, 1); PG8_SCHED; PG8_LDA(At, 0, 0); PG8_STAGEA(PG8_SA(1, 1), a1 + hstepA, voffA);
;     ...
;             const int relax = __builtin_amdgcn_readfirstlane((t == 0 && ui > 0) ? 1 : 0);
;             PG8_WAIT_VR(8, 24, relax); PG8_WAIT_L(0); PG8_BAR; PG8_MMA(0, 0, At, B0); PG8_MMA(0, 1, At, B1); PG8_BAR; PG8_SCHED;
;     ...
;             PG8_WAIT_V(8); PG8_WAIT_L(0); PG8_BAR; PG8_MMA(0, 0, At, B0); PG8_MMA(0, 1, At, B1); PG8_BAR; PG8_SCHED;
;     ...
;             PG8_LDA(At, 0, 1); PG8_STAGEB(PG8_SB(0, 0), b2, voffB); PG8_STAGEB(PG8_SB(0, 1), b2 + hstepB, voffB); PG8_STAGEA(PG8_SA(0, 0), a2, voffA);
;     ...
;             PG8_WAIT_VR(8, 24, relax); PG8_WAIT_L(0); PG8_BAR; PG8_MMA(1, 0, At, B0); PG8_MMA(1, 1, At, B1); PG8_BAR; PG8_SCHED;
;     ...
;             PG8_WAIT_V(8); PG8_WAIT_L(0); PG8_BAR; PG8_MMA(1, 0, At, B0); PG8_MMA(1, 1, At, B1); PG8_BAR; PG8_SCHED;
;     ...
;             PG8_LDB(B0, 1, 0); PG8_LDB(B1, 1, 1); PG8_SCHED; PG8_LDA(At, 1, 0); PG8_STAGEA(PG8_SA(0, 1), a2 + hstepA, voffA);
;             PG8_WAIT_V(8); PG8_WAIT_L(0); PG8_BAR; PG8_MMA(0, 0, At, B0); PG8_MMA(0, 1, At, B1); PG8_BAR; PG8_SCHED;
;             PG8_LDA(At, 1, 1); PG8_STAGEB(PG8_SB(1, 0), b3, voffB); PG8_STAGEB(PG8_SB(1, 1), b3 + hstepB, voffB); PG8_STAGEA(PG8_SA(1, 0), a3, voffA);
;             PG8_WAIT_V(8); PG8_WAIT_L(0); PG8_BAR; PG8_MMA(1, 0, At, B0); PG8_MMA(1, 1, At, B1); PG8_BAR; PG8_SCHED;
	ds_read_b128 v[150:153], v222 offset:32768
	ds_read_b128 v[154:157], v222 offset:33792
	ds_read_b128 v[158:161], v222 offset:34816
	ds_read_b128 v[162:165], v222 offset:35840
	ds_read_b128 v[166:169], v222 offset:49152
	ds_read_b128 v[170:173], v222 offset:50176
	ds_read_b128 v[174:177], v222 offset:51200
	ds_read_b128 v[178:181], v222 offset:52224
	s_add_u32 s6, s42, 0x100000
	s_addc_u32 s7, s43, 0
	s_mov_b32 m0, s73
	ds_read_b128 v[182:185], v148 offset:32768
	ds_read_b128 v[186:189], v148 offset:33792
	ds_read_b128 v[190:193], v148 offset:34816
	ds_read_b128 v[194:197], v148 offset:35840
	ds_read_b128 v[198:201], v148 offset:36864
	ds_read_b128 v[202:205], v148 offset:37888
	ds_read_b128 v[206:209], v148 offset:38912
	global_load_lds_dwordx4 v136, s[6:7]
	s_mov_b32 m0, s82
	ds_read_b128 v[210:213], v148 offset:39936
	global_load_lds_dwordx4 v132, s[6:7]
	s_waitcnt vmcnt(8) lgkmcnt(0)
	s_barrier
	v_mfma_f32_16x16x32_bf16 v[126:129], v[150:153], v[182:185], v[126:129]
	v_mfma_f32_16x16x32_bf16 v[122:125], v[158:161], v[182:185], v[122:125]
	v_mfma_f32_16x16x32_bf16 v[110:113], v[150:153], v[190:193], v[110:113]
	v_mfma_f32_16x16x32_bf16 v[106:109], v[158:161], v[190:193], v[106:109]
	v_mfma_f32_16x16x32_bf16 v[94:97], v[150:153], v[198:201], v[94:97]
	v_mfma_f32_16x16x32_bf16 v[90:93], v[158:161], v[198:201], v[90:93]
	v_mfma_f32_16x16x32_bf16 v[78:81], v[150:153], v[206:209], v[78:81]
	v_mfma_f32_16x16x32_bf16 v[74:77], v[158:161], v[206:209], v[74:77]
	v_mfma_f32_16x16x32_bf16 v[126:129], v[154:157], v[186:189], v[126:129]
	v_mfma_f32_16x16x32_bf16 v[122:125], v[162:165], v[186:189], v[122:125]
	v_mfma_f32_16x16x32_bf16 v[110:113], v[154:157], v[194:197], v[110:113]
	v_mfma_f32_16x16x32_bf16 v[106:109], v[162:165], v[194:197], v[106:109]
	v_mfma_f32_16x16x32_bf16 v[94:97], v[154:157], v[202:205], v[94:97]
	v_mfma_f32_16x16x32_bf16 v[90:93], v[162:165], v[202:205], v[90:93]
	v_mfma_f32_16x16x32_bf16 v[78:81], v[154:157], v[210:213], v[78:81]
	v_mfma_f32_16x16x32_bf16 v[74:77], v[162:165], v[210:213], v[74:77]
	v_mfma_f32_16x16x32_bf16 v[118:121], v[166:169], v[182:185], v[118:121]
	v_mfma_f32_16x16x32_bf16 v[114:117], v[174:177], v[182:185], v[114:117]
	v_mfma_f32_16x16x32_bf16 v[102:105], v[166:169], v[190:193], v[102:105]
	v_mfma_f32_16x16x32_bf16 v[98:101], v[174:177], v[190:193], v[98:101]
	v_mfma_f32_16x16x32_bf16 v[86:89], v[166:169], v[198:201], v[86:89]
	v_mfma_f32_16x16x32_bf16 v[82:85], v[174:177], v[198:201], v[82:85]
	v_mfma_f32_16x16x32_bf16 v[70:73], v[166:169], v[206:209], v[70:73]
	v_mfma_f32_16x16x32_bf16 v[66:69], v[174:177], v[206:209], v[66:69]
	v_mfma_f32_16x16x32_bf16 v[118:121], v[170:173], v[186:189], v[118:121]
	v_mfma_f32_16x16x32_bf16 v[114:117], v[178:181], v[186:189], v[114:117]
	v_mfma_f32_16x16x32_bf16 v[102:105], v[170:173], v[194:197], v[102:105]
	v_mfma_f32_16x16x32_bf16 v[98:101], v[178:181], v[194:197], v[98:101]
	v_mfma_f32_16x16x32_bf16 v[86:89], v[170:173], v[202:205], v[86:89]
	v_mfma_f32_16x16x32_bf16 v[82:85], v[178:181], v[202:205], v[82:85]
	v_mfma_f32_16x16x32_bf16 v[70:73], v[170:173], v[210:213], v[70:73]
	v_mfma_f32_16x16x32_bf16 v[66:69], v[178:181], v[210:213], v[66:69]
	s_barrier
	s_add_i32 s6, s50, 0x18000
	s_mov_b32 m0, s6
	ds_read_b128 v[182:185], v148 offset:49152
	ds_read_b128 v[186:189], v148 offset:50176
	ds_read_b128 v[190:193], v148 offset:51200
	ds_read_b128 v[194:197], v148 offset:52224
	ds_read_b128 v[198:201], v148 offset:53248
	s_add_u32 s100, s16, 0x80
	s_addc_u32 s101, s17, 0
	global_load_lds_dwordx4 v134, s[100:101]
	s_add_i32 m0, s6, 0x2000
	s_add_u32 s6, s16, 0x100080
	s_addc_u32 s7, s17, 0
	s_add_i32 s16, s50, 0x1c000
	global_load_lds_dwordx4 v130, s[100:101]
	s_mov_b32 m0, s16
	ds_read_b128 v[210:213], v148 offset:56320
	global_load_lds_dwordx4 v134, s[6:7]
	s_add_i32 m0, s16, 0x2000
	ds_read_b128 v[206:209], v148 offset:55296
	global_load_lds_dwordx4 v130, s[6:7]
	s_mov_b32 m0, s83
	s_nop 0
	s_add_u32 s100, s42, 0x80
	s_addc_u32 s101, s43, 0
	global_load_lds_dwordx4 v136, s[100:101]
	s_mov_b32 m0, s90
	ds_read_b128 v[202:205], v148 offset:54272
	global_load_lds_dwordx4 v132, s[100:101]
	s_waitcnt vmcnt(8) lgkmcnt(0)
	s_nop 0
	s_barrier
	v_mfma_f32_16x16x32_bf16 v[62:65], v[150:153], v[182:185], v[62:65]
	v_mfma_f32_16x16x32_bf16 v[58:61], v[158:161], v[182:185], v[58:61]
	v_mfma_f32_16x16x32_bf16 v[46:49], v[150:153], v[190:193], v[46:49]
	v_mfma_f32_16x16x32_bf16 v[42:45], v[158:161], v[190:193], v[42:45]
	v_mfma_f32_16x16x32_bf16 v[30:33], v[150:153], v[198:201], v[30:33]
	v_mfma_f32_16x16x32_bf16 v[26:29], v[158:161], v[198:201], v[26:29]
	v_mfma_f32_16x16x32_bf16 v[12:15], v[150:153], v[206:209], v[12:15]
	v_mfma_f32_16x16x32_bf16 v[8:11], v[158:161], v[206:209], v[8:11]
	v_mfma_f32_16x16x32_bf16 v[62:65], v[154:157], v[186:189], v[62:65]
	v_mfma_f32_16x16x32_bf16 v[58:61], v[162:165], v[186:189], v[58:61]
	v_mfma_f32_16x16x32_bf16 v[46:49], v[154:157], v[194:197], v[46:49]
	v_mfma_f32_16x16x32_bf16 v[42:45], v[162:165], v[194:197], v[42:45]
	v_mfma_f32_16x16x32_bf16 v[30:33], v[154:157], v[202:205], v[30:33]
	v_mfma_f32_16x16x32_bf16 v[26:29], v[162:165], v[202:205], v[26:29]
	v_mfma_f32_16x16x32_bf16 v[12:15], v[154:157], v[210:213], v[12:15]
	v_mfma_f32_16x16x32_bf16 v[8:11], v[162:165], v[210:213], v[8:11]
	v_mfma_f32_16x16x32_bf16 v[54:57], v[166:169], v[182:185], v[54:57]
	v_mfma_f32_16x16x32_bf16 v[50:53], v[174:177], v[182:185], v[50:53]
	v_mfma_f32_16x16x32_bf16 v[38:41], v[166:169], v[190:193], v[38:41]
	v_mfma_f32_16x16x32_bf16 v[34:37], v[174:177], v[190:193], v[34:37]
	v_mfma_f32_16x16x32_bf16 v[22:25], v[166:169], v[198:201], v[22:25]
	v_mfma_f32_16x16x32_bf16 v[18:21], v[174:177], v[198:201], v[18:21]
	v_mfma_f32_16x16x32_bf16 v[4:7], v[166:169], v[206:209], v[4:7]
	v_mfma_f32_16x16x32_bf16 v[0:3], v[174:177], v[206:209], v[0:3]
	v_mfma_f32_16x16x32_bf16 v[54:57], v[170:173], v[186:189], v[54:57]
	v_mfma_f32_16x16x32_bf16 v[50:53], v[178:181], v[186:189], v[50:53]
	v_mfma_f32_16x16x32_bf16 v[38:41], v[170:173], v[194:197], v[38:41]
	v_mfma_f32_16x16x32_bf16 v[34:37], v[178:181], v[194:197], v[34:37]
	v_mfma_f32_16x16x32_bf16 v[22:25], v[170:173], v[202:205], v[22:25]
	v_mfma_f32_16x16x32_bf16 v[18:21], v[178:181], v[202:205], v[18:21]
	v_mfma_f32_16x16x32_bf16 v[4:7], v[170:173], v[210:213], v[4:7]
	v_mfma_f32_16x16x32_bf16 v[0:3], v[178:181], v[210:213], v[0:3]
	s_barrier
	s_add_i32 s39, s39, 2
	s_add_u32 s40, s40, 0x100
	s_addc_u32 s41, s41, 0
	s_add_u32 s12, s12, 0x100
	s_addc_u32 s13, s13, 0
	s_cmp_gt_u32 s39, 61
	s_cbranch_scc0 .LBB0_712
	s_and_b64 vcc, exec, s[18:19]
	s_cbranch_vccz .LBB0_715
	s_barrier

; #define PG8_STAGEA(bufoff, gbase, voff) PG8_STAGE_X(bufoff, gbase, voff, AUXA)
; #define PG8_STAGEB(bufoff, gbase, voff) PG8_STAGE_X(bufoff, gbase, voff, AUXB)
; #define PG8_LDA(dst, b, h) do { _Pragma("unroll") for (int m = 0; m < 4; ++m) _Pragma("unroll") for (int k = 0; k < 2; ++k) dst[m][k] = *(const PG8_LAS bf16x8*)(lds + PG8_SA(b, h) + aoff + m * 2048 + k * 1024); } while (0)
; #define PG8_WAIT_V(n) asm volatile("s_waitcnt vmcnt(" #n ")" ::: "memory")
; #define PG8_WAIT_L(n) asm volatile("s_waitcnt lgkmcnt(" #n ")" ::: "memory")
;     ...
;         for (int t = t0; t < nt; t += 2) {
;             const bool last = (t == nt - 2);
;             const char* a1 = cA + (size_t)(t + 1) * kstepA;
;             const char* a2 = last ? nA : cA + (size_t)(t + 2) * kstepA; const char* b2 = last ? nB : cB + (size_t)(t + 2) * kstepB;
;             const char* a3 = a2 + kstepA; const char* b3 = b2 + kstepB;
;             if (last && has_next) S.a_ready(nxt);
;             if constexpr (SP2) {
;             PG8_LDB(B0, 0, 0); PG8_LDB(B1, 0, 1); PG8_SCHED; PG8_LDA(At, 0, 0); PG8_STAGEA(PG8_SA(1, 1), a1 + hstepA, voffA);
;     ...
;             const int relax = __builtin_amdgcn_readfirstlane((t == 0 && ui > 0) ? 1 : 0);
;             PG8_WAIT_VR(8, 24, relax); PG8_WAIT_L(0); PG8_BAR; PG8_MMA(0, 0, At, B0); PG8_MMA(0, 1, At, B1); PG8_BAR; PG8_SCHED;
;     ...
;             PG8_WAIT_V(8); PG8_WAIT_L(0); PG8_BAR; PG8_MMA(0, 0, At, B0); PG8_MMA(0, 1, At, B1); PG8_BAR; PG8_SCHED;
;     ...
;             PG8_LDA(At, 0, 1); PG8_STAGEB(PG8_SB(0, 0), b2, voffB); PG8_STAGEB(PG8_SB(0, 1), b2 + hstepB, voffB); PG8_STAGEA(PG8_SA(0, 0), a2, voffA);
;     ...
;             PG8_WAIT_VR(8, 24, relax); PG8_WAIT_L(0); PG8_BAR; PG8_MMA(1, 0, At, B0); PG8_MMA(1, 1, At, B1); PG8_BAR; PG8_SCHED;
;     ...
;             PG8_WAIT_V(8); PG8_WAIT_L(0); PG8_BAR; PG8_MMA(1, 0, At, B0); PG8_MMA(1, 1, At, B1); PG8_BAR; PG8_SCHED;
;     ...
;             PG8_LDB(B0, 1, 0); PG8_LDB(B1, 1, 1); PG8_SCHED; PG8_LDA(At, 1, 0); PG8_STAGEA(PG8_SA(0, 1), a2 + hstepA, voffA);
;             PG8_WAIT_V(8); PG8_WAIT_L(0); PG8_BAR; PG8_MMA(0, 0, At, B0); PG8_MMA(0, 1, At, B1); PG8_BAR; PG8_SCHED;
;             PG8_LDA(At, 1, 1); PG8_STAGEB(PG8_SB(1, 0), b3, voffB); PG8_STAGEB(PG8_SB(1, 1), b3 + hstepB, voffB); PG8_STAGEA(PG8_SA(1, 0), a3, voffA);
;             PG8_WAIT_V(8); PG8_WAIT_L(0); PG8_BAR; PG8_MMA(1, 0, At, B0); PG8_MMA(1, 1, At, B1); PG8_BAR; PG8_SCHED;
.LBB0_847:
	s_ashr_i32 s11, s10, 31
	s_lshl_b64 s[18:19], s[10:11], 23
	s_add_u32 s18, s62, s18
	s_addc_u32 s19, s63, s19
	s_and_b64 s[22:23], s[20:21], exec
	s_cselect_b32 s11, s19, s1
	s_cselect_b32 s73, s18, s0
	s_ashr_i32 s15, s14, 31
	s_lshl_b64 s[22:23], s[14:15], 23
	s_add_u32 s22, s12, s22
	s_addc_u32 s23, s13, s23
	s_and_b64 s[24:25], s[20:21], exec
	s_cselect_b32 s15, s23, s17
	s_cselect_b32 s78, s22, s16
	s_add_u32 s24, s0, 0xc000
	s_addc_u32 s25, s1, 0
	s_add_u32 s0, s16, 0x10000
	s_addc_u32 s1, s17, 0
	s_mov_b32 s82, -2
	s_waitcnt lgkmcnt(0)
	s_add_u32 s16, s24, 0x4000
	s_addc_u32 s17, s25, 0
	s_cmpk_eq_i32 s82, 0xfc
	s_cselect_b32 s36, s73, s16
	s_cselect_b32 s37, s11, s17
	s_cselect_b32 s16, s78, s0
	s_cselect_b32 s17, s15, s1
	s_add_u32 s26, s36, 0x8000
	s_addc_u32 s27, s37, 0
	s_add_i32 s83, 0, 0x10000
	s_add_i32 s94, 0, 0x14000
	v_add_u32_e32 v152, s83, v157
	v_add_u32_e32 v174, s94, v157
	ds_read_b128 v[130:133], v152
	ds_read_b128 v[134:137], v152 offset:1024
	ds_read_b128 v[148:151], v152 offset:2048
	ds_read_b128 v[152:155], v152 offset:3072
	ds_read_b128 v[162:165], v174
	ds_read_b128 v[166:169], v174 offset:1024
	ds_read_b128 v[170:173], v174 offset:2048
	ds_read_b128 v[174:177], v174 offset:3072
	v_lshl_add_u64 v[210:211], s[24:25], 0, v[144:145]
	s_add_i32 m0, s39, 0xc000
	ds_read_b128 v[178:181], v161
	ds_read_b128 v[182:185], v161 offset:1024
	ds_read_b128 v[186:189], v161 offset:2048
	ds_read_b128 v[190:193], v161 offset:3072
	ds_read_b128 v[194:197], v161 offset:4096
	ds_read_b128 v[198:201], v161 offset:5120
	ds_read_b128 v[202:205], v161 offset:6144
	ds_read_b128 v[206:209], v161 offset:7168
	global_load_lds_dwordx4 v[210:211], off
	v_lshl_add_u64 v[210:211], s[24:25], 0, v[146:147]
	s_add_i32 m0, s39, 0xe000
	s_nop 0
	global_load_lds_dwordx4 v[210:211], off
	s_waitcnt vmcnt(8) lgkmcnt(0)
	s_nop 0
	s_barrier
	v_mfma_f32_16x16x32_bf16 v[126:129], v[130:133], v[178:181], 0
	v_mfma_f32_16x16x32_bf16 v[122:125], v[148:151], v[178:181], 0
	v_mfma_f32_16x16x32_bf16 v[110:113], v[130:133], v[186:189], 0
	v_mfma_f32_16x16x32_bf16 v[106:109], v[148:151], v[186:189], 0
	v_mfma_f32_16x16x32_bf16 v[94:97], v[130:133], v[194:197], 0
	v_mfma_f32_16x16x32_bf16 v[90:93], v[148:151], v[194:197], 0
	v_mfma_f32_16x16x32_bf16 v[78:81], v[130:133], v[202:205], 0
	v_mfma_f32_16x16x32_bf16 v[74:77], v[148:151], v[202:205], 0
	v_mfma_f32_16x16x32_bf16 v[126:129], v[134:137], v[182:185], v[126:129]
	v_mfma_f32_16x16x32_bf16 v[122:125], v[152:155], v[182:185], v[122:125]
	v_mfma_f32_16x16x32_bf16 v[110:113], v[134:137], v[190:193], v[110:113]
	v_mfma_f32_16x16x32_bf16 v[106:109], v[152:155], v[190:193], v[106:109]
	v_mfma_f32_16x16x32_bf16 v[94:97], v[134:137], v[198:201], v[94:97]
	v_mfma_f32_16x16x32_bf16 v[90:93], v[152:155], v[198:201], v[90:93]
	v_mfma_f32_16x16x32_bf16 v[78:81], v[134:137], v[206:209], v[78:81]
	v_mfma_f32_16x16x32_bf16 v[74:77], v[152:155], v[206:209], v[74:77]
	v_mfma_f32_16x16x32_bf16 v[118:121], v[162:165], v[178:181], 0
	v_mfma_f32_16x16x32_bf16 v[114:117], v[170:173], v[178:181], 0
	v_mfma_f32_16x16x32_bf16 v[102:105], v[162:165], v[186:189], 0
	v_mfma_f32_16x16x32_bf16 v[98:101], v[170:173], v[186:189], 0
	v_mfma_f32_16x16x32_bf16 v[86:89], v[162:165], v[194:197], 0
	v_mfma_f32_16x16x32_bf16 v[82:85], v[170:173], v[194:197], 0
	v_mfma_f32_16x16x32_bf16 v[70:73], v[162:165], v[202:205], 0
	v_mfma_f32_16x16x32_bf16 v[66:69], v[170:173], v[202:205], 0
	v_mfma_f32_16x16x32_bf16 v[118:121], v[166:169], v[182:185], v[118:121]
	v_mfma_f32_16x16x32_bf16 v[114:117], v[174:177], v[182:185], v[114:117]
	v_mfma_f32_16x16x32_bf16 v[102:105], v[166:169], v[190:193], v[102:105]
	v_mfma_f32_16x16x32_bf16 v[98:101], v[174:177], v[190:193], v[98:101]
	v_mfma_f32_16x16x32_bf16 v[86:89], v[166:169], v[198:201], v[86:89]
	v_mfma_f32_16x16x32_bf16 v[82:85], v[174:177], v[198:201], v[82:85]
	v_mfma_f32_16x16x32_bf16 v[70:73], v[166:169], v[206:209], v[70:73]
	v_mfma_f32_16x16x32_bf16 v[66:69], v[174:177], v[206:209], v[66:69]
	s_barrier
	s_add_i32 s83, s83, s38
	v_lshl_add_u64 v[210:211], s[16:17], 0, v[16:17]
	s_mov_b32 m0, s83
	ds_read_b128 v[178:181], v161 offset:16384
	ds_read_b128 v[182:185], v161 offset:17408
	ds_read_b128 v[186:189], v161 offset:18432
	ds_read_b128 v[190:193], v161 offset:19456
	ds_read_b128 v[194:197], v161 offset:20480
	ds_read_b128 v[198:201], v161 offset:21504
	ds_read_b128 v[202:205], v161 offset:22528
	ds_read_b128 v[206:209], v161 offset:23552
	global_load_lds_dwordx4 v[210:211], off
	s_add_i32 m0, s83, 0x2000
	s_add_u32 s90, s16, 0x4000
	v_lshl_add_u64 v[210:211], s[16:17], 0, v[138:139]
	s_addc_u32 s91, s17, 0
	s_add_i32 s83, s94, s38
	global_load_lds_dwordx4 v[210:211], off
	v_lshl_add_u64 v[210:211], s[90:91], 0, v[16:17]
	s_mov_b32 m0, s83
	s_nop 0
	global_load_lds_dwordx4 v[210:211], off
	v_lshl_add_u64 v[210:211], s[90:91], 0, v[138:139]
	s_add_i32 m0, s83, 0x2000
	s_nop 0
	global_load_lds_dwordx4 v[210:211], off
	v_lshl_add_u64 v[210:211], s[36:37], 0, v[142:143]
	s_mov_b32 m0, s39
	s_nop 0
	global_load_lds_dwordx4 v[210:211], off
	v_lshl_add_u64 v[210:211], s[36:37], 0, v[140:141]
	s_mov_b32 m0, s40
	s_nop 0
	global_load_lds_dwordx4 v[210:211], off
	s_waitcnt vmcnt(8) lgkmcnt(0)
	s_barrier
; #define PG8_STAGEA(bufoff, gbase, voff) PG8_STAGE_X(bufoff, gbase, voff, AUXA)
; #define PG8_STAGEB(bufoff, gbase, voff) PG8_STAGE_X(bufoff, gbase, voff, AUXB)
; #define PG8_LDA(dst, b, h) do { _Pragma("unroll") for (int m = 0; m < 4; ++m) _Pragma("unroll") for (int k = 0; k < 2; ++k) dst[m][k] = *(const PG8_LAS bf16x8*)(lds + PG8_SA(b, h) + aoff + m * 2048 + k * 1024); } while (0)
; #define PG8_LDB(dst, b, h) do { _Pragma("unroll") for (int n = 0; n < 2; ++n) _Pragma("unroll") for (int k = 0; k < 2; ++k) dst[n][k] = *(const PG8_LAS bf16x8*)(lds + PG8_SB(b, h) + boff + n * 2048 + k * 1024); } while (0)
; #define PG8_MMA(ai, bj, At, Bt) do { if (GEMM_PRIO_MODE == 0) __builtin_amdgcn_s_setprio(1); PG8_MMA_LOOPS \
;         acc[ai][bj][m][n] = __builtin_amdgcn_mfma_f32_16x16x32_bf16(Bt[n][k], At[m][k], acc[ai][bj][m][n], 0, 0, 0); if (GEMM_PRIO_MODE == 0) __builtin_amdgcn_s_setprio(0); } while (0)
; #define PG8_WAIT_V(n) asm volatile("s_waitcnt vmcnt(" #n ")" ::: "memory")
;     ...
;             PG8_LDB(B0, 0, 0); PG8_LDB(B1, 0, 1); PG8_SCHED; PG8_LDA(At, 0, 0); PG8_STAGEA(PG8_SA(1, 1), a1 + hstepA, voffA);
;     ...
;             const int relax = __builtin_amdgcn_readfirstlane((t == 0 && ui > 0) ? 1 : 0);
;             PG8_WAIT_VR(8, 24, relax); PG8_WAIT_L(0); PG8_BAR; PG8_MMA(0, 0, At, B0); PG8_MMA(0, 1, At, B1); PG8_BAR; PG8_SCHED;
;     ...
;             PG8_WAIT_V(8); PG8_WAIT_L(0); PG8_BAR; PG8_MMA(0, 0, At, B0); PG8_MMA(0, 1, At, B1); PG8_BAR; PG8_SCHED;
;     ...
;             PG8_LDA(At, 0, 1); PG8_STAGEB(PG8_SB(0, 0), b2, voffB); PG8_STAGEB(PG8_SB(0, 1), b2 + hstepB, voffB); PG8_STAGEA(PG8_SA(0, 0), a2, voffA);
;     ...
;             PG8_WAIT_VR(8, 24, relax); PG8_WAIT_L(0); PG8_BAR; PG8_MMA(1, 0, At, B0); PG8_MMA(1, 1, At, B1); PG8_BAR; PG8_SCHED;
;     ...
;             PG8_WAIT_V(8); PG8_WAIT_L(0); PG8_BAR; PG8_MMA(1, 0, At, B0); PG8_MMA(1, 1, At, B1); PG8_BAR; PG8_SCHED;
;     ...
;             PG8_LDB(B0, 1, 0); PG8_LDB(B1, 1, 1); PG8_SCHED; PG8_LDA(At, 1, 0); PG8_STAGEA(PG8_SA(0, 1), a2 + hstepA, voffA);
;             PG8_WAIT_V(8); PG8_WAIT_L(0); PG8_BAR; PG8_MMA(0, 0, At, B0); PG8_MMA(0, 1, At, B1); PG8_BAR; PG8_SCHED;
;             PG8_LDA(At, 1, 1); PG8_STAGEB(PG8_SB(1, 0), b3, voffB); PG8_STAGEB(PG8_SB(1, 1), b3 + hstepB, voffB); PG8_STAGEA(PG8_SA(1, 0), a3, voffA);
;             PG8_WAIT_V(8); PG8_WAIT_L(0); PG8_BAR; PG8_MMA(1, 0, At, B0); PG8_MMA(1, 1, At, B1); PG8_BAR; PG8_SCHED;
	v_mfma_f32_16x16x32_bf16 v[62:65], v[130:133], v[178:181], 0
	v_mfma_f32_16x16x32_bf16 v[58:61], v[148:151], v[178:181], 0
	v_mfma_f32_16x16x32_bf16 v[46:49], v[130:133], v[186:189], 0
	v_mfma_f32_16x16x32_bf16 v[42:45], v[148:151], v[186:189], 0
	v_mfma_f32_16x16x32_bf16 v[30:33], v[130:133], v[194:197], 0
	v_mfma_f32_16x16x32_bf16 v[26:29], v[148:151], v[194:197], 0
	v_mfma_f32_16x16x32_bf16 v[12:15], v[130:133], v[202:205], 0
	v_mfma_f32_16x16x32_bf16 v[8:11], v[148:151], v[202:205], 0
	v_mfma_f32_16x16x32_bf16 v[62:65], v[134:137], v[182:185], v[62:65]
	v_mfma_f32_16x16x32_bf16 v[58:61], v[152:155], v[182:185], v[58:61]
	v_mfma_f32_16x16x32_bf16 v[46:49], v[134:137], v[190:193], v[46:49]
	v_mfma_f32_16x16x32_bf16 v[42:45], v[152:155], v[190:193], v[42:45]
	v_mfma_f32_16x16x32_bf16 v[30:33], v[134:137], v[198:201], v[30:33]
	v_mfma_f32_16x16x32_bf16 v[26:29], v[152:155], v[198:201], v[26:29]
	v_mfma_f32_16x16x32_bf16 v[12:15], v[134:137], v[206:209], v[12:15]
	v_mfma_f32_16x16x32_bf16 v[8:11], v[152:155], v[206:209], v[8:11]
	v_mfma_f32_16x16x32_bf16 v[54:57], v[162:165], v[178:181], 0
	v_mfma_f32_16x16x32_bf16 v[50:53], v[170:173], v[178:181], 0
	v_mfma_f32_16x16x32_bf16 v[38:41], v[162:165], v[186:189], 0
	v_mfma_f32_16x16x32_bf16 v[34:37], v[170:173], v[186:189], 0
	v_mfma_f32_16x16x32_bf16 v[22:25], v[162:165], v[194:197], 0
	v_mfma_f32_16x16x32_bf16 v[18:21], v[170:173], v[194:197], 0
	v_mfma_f32_16x16x32_bf16 v[4:7], v[162:165], v[202:205], 0
	v_mfma_f32_16x16x32_bf16 v[0:3], v[170:173], v[202:205], 0
	v_mfma_f32_16x16x32_bf16 v[54:57], v[166:169], v[182:185], v[54:57]
	v_mfma_f32_16x16x32_bf16 v[50:53], v[174:177], v[182:185], v[50:53]
	v_mfma_f32_16x16x32_bf16 v[38:41], v[166:169], v[190:193], v[38:41]
	v_mfma_f32_16x16x32_bf16 v[34:37], v[174:177], v[190:193], v[34:37]
	v_mfma_f32_16x16x32_bf16 v[22:25], v[166:169], v[198:201], v[22:25]
	v_mfma_f32_16x16x32_bf16 v[18:21], v[174:177], v[198:201], v[18:21]
	v_mfma_f32_16x16x32_bf16 v[4:7], v[166:169], v[206:209], v[4:7]
	v_mfma_f32_16x16x32_bf16 v[0:3], v[174:177], v[206:209], v[0:3]
	s_barrier
	s_add_i32 s83, 0, 0x18000
	s_add_i32 s90, 0, 0x1c000
	v_add_u32_e32 v152, s83, v157
	v_add_u32_e32 v174, s90, v157
	ds_read_b128 v[130:133], v152
	ds_read_b128 v[134:137], v152 offset:1024
	ds_read_b128 v[148:151], v152 offset:2048
	ds_read_b128 v[152:155], v152 offset:3072
	ds_read_b128 v[162:165], v174
	ds_read_b128 v[166:169], v174 offset:1024
	ds_read_b128 v[170:173], v174 offset:2048
	ds_read_b128 v[174:177], v174 offset:3072
	s_add_u32 s36, s36, 0x4000
	s_addc_u32 s37, s37, 0
	s_mov_b32 m0, s41
	v_lshl_add_u64 v[210:211], s[36:37], 0, v[142:143]
	ds_read_b128 v[178:181], v161 offset:32768
	ds_read_b128 v[182:185], v161 offset:33792
	ds_read_b128 v[186:189], v161 offset:34816
	ds_read_b128 v[190:193], v161 offset:35840
	ds_read_b128 v[194:197], v161 offset:36864
	ds_read_b128 v[198:201], v161 offset:37888
	ds_read_b128 v[202:205], v161 offset:38912
	ds_read_b128 v[206:209], v161 offset:39936
	global_load_lds_dwordx4 v[210:211], off
	v_lshl_add_u64 v[210:211], s[36:37], 0, v[140:141]
	s_mov_b32 m0, s42
	s_nop 0
	global_load_lds_dwordx4 v[210:211], off
	s_waitcnt vmcnt(8) lgkmcnt(0)
	s_nop 0
	s_nop 0
	s_nop 0
	s_barrier
	v_mfma_f32_16x16x32_bf16 v[126:129], v[130:133], v[178:181], v[126:129]
	v_mfma_f32_16x16x32_bf16 v[122:125], v[148:151], v[178:181], v[122:125]
	v_mfma_f32_16x16x32_bf16 v[110:113], v[130:133], v[186:189], v[110:113]
	v_mfma_f32_16x16x32_bf16 v[106:109], v[148:151], v[186:189], v[106:109]
	v_mfma_f32_16x16x32_bf16 v[94:97], v[130:133], v[194:197], v[94:97]
	v_mfma_f32_16x16x32_bf16 v[90:93], v[148:151], v[194:197], v[90:93]
	v_mfma_f32_16x16x32_bf16 v[78:81], v[130:133], v[202:205], v[78:81]
	v_mfma_f32_16x16x32_bf16 v[74:77], v[148:151], v[202:205], v[74:77]
	v_mfma_f32_16x16x32_bf16 v[126:129], v[134:137], v[182:185], v[126:129]
	v_mfma_f32_16x16x32_bf16 v[122:125], v[152:155], v[182:185], v[122:125]
	v_mfma_f32_16x16x32_bf16 v[110:113], v[134:137], v[190:193], v[110:113]
	v_mfma_f32_16x16x32_bf16 v[106:109], v[152:155], v[190:193], v[106:109]
	v_mfma_f32_16x16x32_bf16 v[94:97], v[134:137], v[198:201], v[94:97]
	v_mfma_f32_16x16x32_bf16 v[90:93], v[152:155], v[198:201], v[90:93]
	v_mfma_f32_16x16x32_bf16 v[78:81], v[134:137], v[206:209], v[78:81]
	v_mfma_f32_16x16x32_bf16 v[74:77], v[152:155], v[206:209], v[74:77]
	v_mfma_f32_16x16x32_bf16 v[118:121], v[162:165], v[178:181], v[118:121]
	v_mfma_f32_16x16x32_bf16 v[114:117], v[170:173], v[178:181], v[114:117]
	v_mfma_f32_16x16x32_bf16 v[102:105], v[162:165], v[186:189], v[102:105]
	v_mfma_f32_16x16x32_bf16 v[98:101], v[170:173], v[186:189], v[98:101]
	v_mfma_f32_16x16x32_bf16 v[86:89], v[162:165], v[194:197], v[86:89]
	v_mfma_f32_16x16x32_bf16 v[82:85], v[170:173], v[194:197], v[82:85]
	v_mfma_f32_16x16x32_bf16 v[70:73], v[162:165], v[202:205], v[70:73]
	v_mfma_f32_16x16x32_bf16 v[66:69], v[170:173], v[202:205], v[66:69]
	v_mfma_f32_16x16x32_bf16 v[118:121], v[166:169], v[182:185], v[118:121]
	v_mfma_f32_16x16x32_bf16 v[114:117], v[174:177], v[182:185], v[114:117]
	v_mfma_f32_16x16x32_bf16 v[102:105], v[166:169], v[190:193], v[102:105]
	v_mfma_f32_16x16x32_bf16 v[98:101], v[174:177], v[190:193], v[98:101]
	v_mfma_f32_16x16x32_bf16 v[86:89], v[166:169], v[198:201], v[86:89]
	v_mfma_f32_16x16x32_bf16 v[82:85], v[174:177], v[198:201], v[82:85]
	v_mfma_f32_16x16x32_bf16 v[70:73], v[166:169], v[206:209], v[70:73]
	v_mfma_f32_16x16x32_bf16 v[66:69], v[174:177], v[206:209], v[66:69]
	s_barrier
; #define PG8_STAGEA(bufoff, gbase, voff) PG8_STAGE_X(bufoff, gbase, voff, AUXA)
; #define PG8_STAGEB(bufoff, gbase, voff) PG8_STAGE_X(bufoff, gbase, voff, AUXB)
; #define PG8_LDA(dst, b, h) do { _Pragma("unroll") for (int m = 0; m < 4; ++m) _Pragma("unroll") for (int k = 0; k < 2; ++k) dst[m][k] = *(const PG8_LAS bf16x8*)(lds + PG8_SA(b, h) + aoff + m * 2048 + k * 1024); } while (0)
; #define PG8_LDB(dst, b, h) do { _Pragma("unroll") for (int n = 0; n < 2; ++n) _Pragma("unroll") for (int k = 0; k < 2; ++k) dst[n][k] = *(const PG8_LAS bf16x8*)(lds + PG8_SB(b, h) + boff + n * 2048 + k * 1024); } while (0)
; #define PG8_MMA(ai, bj, At, Bt) do { if (GEMM_PRIO_MODE == 0) __builtin_amdgcn_s_setprio(1); PG8_MMA_LOOPS \
;         acc[ai][bj][m][n] = __builtin_amdgcn_mfma_f32_16x16x32_bf16(Bt[n][k], At[m][k], acc[ai][bj][m][n], 0, 0, 0); if (GEMM_PRIO_MODE == 0) __builtin_amdgcn_s_setprio(0); } while (0)
; #define PG8_WAIT_V(n) asm volatile("s_waitcnt vmcnt(" #n ")" ::: "memory")
;     ...
;             PG8_LDB(B0, 0, 0); PG8_LDB(B1, 0, 1); PG8_SCHED; PG8_LDA(At, 0, 0); PG8_STAGEA(PG8_SA(1, 1), a1 + hstepA, voffA);
;     ...
;             const int relax = __builtin_amdgcn_readfirstlane((t == 0 && ui > 0) ? 1 : 0);
;             PG8_WAIT_VR(8, 24, relax); PG8_WAIT_L(0); PG8_BAR; PG8_MMA(0, 0, At, B0); PG8_MMA(0, 1, At, B1); PG8_BAR; PG8_SCHED;
;     ...
;             PG8_WAIT_V(8); PG8_WAIT_L(0); PG8_BAR; PG8_MMA(0, 0, At, B0); PG8_MMA(0, 1, At, B1); PG8_BAR; PG8_SCHED;
;     ...
;             PG8_LDA(At, 0, 1); PG8_STAGEB(PG8_SB(0, 0), b2, voffB); PG8_STAGEB(PG8_SB(0, 1), b2 + hstepB, voffB); PG8_STAGEA(PG8_SA(0, 0), a2, voffA);
;     ...
;             PG8_WAIT_VR(8, 24, relax); PG8_WAIT_L(0); PG8_BAR; PG8_MMA(1, 0, At, B0); PG8_MMA(1, 1, At, B1); PG8_BAR; PG8_SCHED;
;     ...
;             PG8_WAIT_V(8); PG8_WAIT_L(0); PG8_BAR; PG8_MMA(1, 0, At, B0); PG8_MMA(1, 1, At, B1); PG8_BAR; PG8_SCHED;
;     ...
;             PG8_LDB(B0, 1, 0); PG8_LDB(B1, 1, 1); PG8_SCHED; PG8_LDA(At, 1, 0); PG8_STAGEA(PG8_SA(0, 1), a2 + hstepA, voffA);
;             PG8_WAIT_V(8); PG8_WAIT_L(0); PG8_BAR; PG8_MMA(0, 0, At, B0); PG8_MMA(0, 1, At, B1); PG8_BAR; PG8_SCHED;
;             PG8_LDA(At, 1, 1); PG8_STAGEB(PG8_SB(1, 0), b3, voffB); PG8_STAGEB(PG8_SB(1, 1), b3 + hstepB, voffB); PG8_STAGEA(PG8_SA(1, 0), a3, voffA);
;             PG8_WAIT_V(8); PG8_WAIT_L(0); PG8_BAR; PG8_MMA(1, 0, At, B0); PG8_MMA(1, 1, At, B1); PG8_BAR; PG8_SCHED;
	s_add_u32 s36, s16, 0x8000
	s_addc_u32 s37, s17, 0
	s_add_i32 s83, s83, s38
	v_lshl_add_u64 v[210:211], s[36:37], 0, v[16:17]
	s_mov_b32 m0, s83
	ds_read_b128 v[178:181], v161 offset:49152
	ds_read_b128 v[182:185], v161 offset:50176
	ds_read_b128 v[186:189], v161 offset:51200
	ds_read_b128 v[190:193], v161 offset:52224
	ds_read_b128 v[194:197], v161 offset:53248
	ds_read_b128 v[198:201], v161 offset:54272
	ds_read_b128 v[202:205], v161 offset:55296
	ds_read_b128 v[206:209], v161 offset:56320
	global_load_lds_dwordx4 v[210:211], off
	s_add_i32 m0, s83, 0x2000
	s_add_u32 s16, s16, 0xc000
	v_lshl_add_u64 v[210:211], s[36:37], 0, v[138:139]
	s_addc_u32 s17, s17, 0
	s_add_i32 s36, s90, s38
	global_load_lds_dwordx4 v[210:211], off
	v_lshl_add_u64 v[210:211], s[16:17], 0, v[16:17]
	s_mov_b32 m0, s36
	s_nop 0
	global_load_lds_dwordx4 v[210:211], off
	v_lshl_add_u64 v[210:211], s[16:17], 0, v[138:139]
	s_add_i32 m0, s36, 0x2000
	s_nop 0
	global_load_lds_dwordx4 v[210:211], off
	v_lshl_add_u64 v[210:211], s[26:27], 0, v[142:143]
	s_mov_b32 m0, s50
	s_nop 0
	global_load_lds_dwordx4 v[210:211], off
	v_lshl_add_u64 v[210:211], s[26:27], 0, v[140:141]
	s_mov_b32 m0, s51
	s_nop 0
	global_load_lds_dwordx4 v[210:211], off
	s_waitcnt vmcnt(8) lgkmcnt(0)
	s_nop 0
	s_barrier
	v_mfma_f32_16x16x32_bf16 v[62:65], v[130:133], v[178:181], v[62:65]
	v_mfma_f32_16x16x32_bf16 v[58:61], v[148:151], v[178:181], v[58:61]
	v_mfma_f32_16x16x32_bf16 v[46:49], v[130:133], v[186:189], v[46:49]
	v_mfma_f32_16x16x32_bf16 v[42:45], v[148:151], v[186:189], v[42:45]
	v_mfma_f32_16x16x32_bf16 v[30:33], v[130:133], v[194:197], v[30:33]
	v_mfma_f32_16x16x32_bf16 v[26:29], v[148:151], v[194:197], v[26:29]
	v_mfma_f32_16x16x32_bf16 v[12:15], v[130:133], v[202:205], v[12:15]
	v_mfma_f32_16x16x32_bf16 v[8:11], v[148:151], v[202:205], v[8:11]
	v_mfma_f32_16x16x32_bf16 v[62:65], v[134:137], v[182:185], v[62:65]
	v_mfma_f32_16x16x32_bf16 v[58:61], v[152:155], v[182:185], v[58:61]
	v_mfma_f32_16x16x32_bf16 v[46:49], v[134:137], v[190:193], v[46:49]
	v_mfma_f32_16x16x32_bf16 v[42:45], v[152:155], v[190:193], v[42:45]
	v_mfma_f32_16x16x32_bf16 v[30:33], v[134:137], v[198:201], v[30:33]
	v_mfma_f32_16x16x32_bf16 v[26:29], v[152:155], v[198:201], v[26:29]
	v_mfma_f32_16x16x32_bf16 v[12:15], v[134:137], v[206:209], v[12:15]
	v_mfma_f32_16x16x32_bf16 v[8:11], v[152:155], v[206:209], v[8:11]
	v_mfma_f32_16x16x32_bf16 v[54:57], v[162:165], v[178:181], v[54:57]
	v_mfma_f32_16x16x32_bf16 v[50:53], v[170:173], v[178:181], v[50:53]
	v_mfma_f32_16x16x32_bf16 v[38:41], v[162:165], v[186:189], v[38:41]
	v_mfma_f32_16x16x32_bf16 v[34:37], v[170:173], v[186:189], v[34:37]
	v_mfma_f32_16x16x32_bf16 v[22:25], v[162:165], v[194:197], v[22:25]
	v_mfma_f32_16x16x32_bf16 v[18:21], v[170:173], v[194:197], v[18:21]
	v_mfma_f32_16x16x32_bf16 v[4:7], v[162:165], v[202:205], v[4:7]
	v_mfma_f32_16x16x32_bf16 v[0:3], v[170:173], v[202:205], v[0:3]
	v_mfma_f32_16x16x32_bf16 v[54:57], v[166:169], v[182:185], v[54:57]
	v_mfma_f32_16x16x32_bf16 v[50:53], v[174:177], v[182:185], v[50:53]
	v_mfma_f32_16x16x32_bf16 v[38:41], v[166:169], v[190:193], v[38:41]
	v_mfma_f32_16x16x32_bf16 v[34:37], v[174:177], v[190:193], v[34:37]
	v_mfma_f32_16x16x32_bf16 v[22:25], v[166:169], v[198:201], v[22:25]
	v_mfma_f32_16x16x32_bf16 v[18:21], v[174:177], v[198:201], v[18:21]
	v_mfma_f32_16x16x32_bf16 v[4:7], v[166:169], v[206:209], v[4:7]
	v_mfma_f32_16x16x32_bf16 v[0:3], v[174:177], v[206:209], v[0:3]
	s_barrier
	s_add_i32 s82, s82, 2
	s_add_u32 s24, s24, 0x10000
	s_addc_u32 s25, s25, 0
	s_add_u32 s0, s0, 0x10000
	s_addc_u32 s1, s1, 0
	v_add_u32_e32 v212, 0x10000, v157
.LBB0_848:
	s_add_u32 s16, s24, 0x4000
	s_addc_u32 s17, s25, 0
	s_cmpk_eq_i32 s82, 0xfc
	s_cselect_b32 s36, s73, s16
	s_cselect_b32 s37, s11, s17
	s_cselect_b32 s16, s78, s0
	s_cselect_b32 s17, s15, s1
	s_add_u32 s26, s36, 0x8000
	s_addc_u32 s27, s37, 0
	s_add_i32 s94, 0, 0x14000
	ds_read_b128 v[130:133], v212
	ds_read_b128 v[134:137], v212 offset:1024
	ds_read_b128 v[148:151], v212 offset:2048
	ds_read_b128 v[152:155], v212 offset:3072
	ds_read_b128 v[162:165], v212 offset:16384
	ds_read_b128 v[166:169], v212 offset:17408
	ds_read_b128 v[170:173], v212 offset:18432
	ds_read_b128 v[174:177], v212 offset:19456
	s_add_i32 m0, s39, 0xc000
	ds_read_b128 v[178:181], v161
	ds_read_b128 v[182:185], v161 offset:1024
	ds_read_b128 v[186:189], v161 offset:2048
	ds_read_b128 v[190:193], v161 offset:3072
	ds_read_b128 v[194:197], v161 offset:4096
	ds_read_b128 v[198:201], v161 offset:5120
	ds_read_b128 v[202:205], v161 offset:6144
	global_load_lds_dwordx4 v144, s[24:25]
	s_add_i32 m0, s39, 0xe000
	ds_read_b128 v[206:209], v161 offset:7168
	global_load_lds_dwordx4 v146, s[24:25]
	s_waitcnt vmcnt(8) lgkmcnt(0)
	s_nop 0
	s_barrier
; #define PG8_STAGEA(bufoff, gbase, voff) PG8_STAGE_X(bufoff, gbase, voff, AUXA)
; #define PG8_STAGEB(bufoff, gbase, voff) PG8_STAGE_X(bufoff, gbase, voff, AUXB)
; #define PG8_LDA(dst, b, h) do { _Pragma("unroll") for (int m = 0; m < 4; ++m) _Pragma("unroll") for (int k = 0; k < 2; ++k) dst[m][k] = *(const PG8_LAS bf16x8*)(lds + PG8_SA(b, h) + aoff + m * 2048 + k * 1024); } while (0)
; #define PG8_LDB(dst, b, h) do { _Pragma("unroll") for (int n = 0; n < 2; ++n) _Pragma("unroll") for (int k = 0; k < 2; ++k) dst[n][k] = *(const PG8_LAS bf16x8*)(lds + PG8_SB(b, h) + boff + n * 2048 + k * 1024); } while (0)
; #define PG8_MMA(ai, bj, At, Bt) do { if (GEMM_PRIO_MODE == 0) __builtin_amdgcn_s_setprio(1); PG8_MMA_LOOPS \
;         acc[ai][bj][m][n] = __builtin_amdgcn_mfma_f32_16x16x32_bf16(Bt[n][k], At[m][k], acc[ai][bj][m][n], 0, 0, 0); if (GEMM_PRIO_MODE == 0) __builtin_amdgcn_s_setprio(0); } while (0)
; #define PG8_WAIT_V(n) asm volatile("s_waitcnt vmcnt(" #n ")" ::: "memory")
;     ...
;             PG8_LDB(B0, 0, 0); PG8_LDB(B1, 0, 1); PG8_SCHED; PG8_LDA(At, 0, 0); PG8_STAGEA(PG8_SA(1, 1), a1 + hstepA, voffA);
;     ...
;             const int relax = __builtin_amdgcn_readfirstlane((t == 0 && ui > 0) ? 1 : 0);
;             PG8_WAIT_VR(8, 24, relax); PG8_WAIT_L(0); PG8_BAR; PG8_MMA(0, 0, At, B0); PG8_MMA(0, 1, At, B1); PG8_BAR; PG8_SCHED;
;     ...
;             PG8_WAIT_V(8); PG8_WAIT_L(0); PG8_BAR; PG8_MMA(0, 0, At, B0); PG8_MMA(0, 1, At, B1); PG8_BAR; PG8_SCHED;
;     ...
;             PG8_LDA(At, 0, 1); PG8_STAGEB(PG8_SB(0, 0), b2, voffB); PG8_STAGEB(PG8_SB(0, 1), b2 + hstepB, voffB); PG8_STAGEA(PG8_SA(0, 0), a2, voffA);
;     ...
;             PG8_WAIT_VR(8, 24, relax); PG8_WAIT_L(0); PG8_BAR; PG8_MMA(1, 0, At, B0); PG8_MMA(1, 1, At, B1); PG8_BAR; PG8_SCHED;
;     ...
;             PG8_WAIT_V(8); PG8_WAIT_L(0); PG8_BAR; PG8_MMA(1, 0, At, B0); PG8_MMA(1, 1, At, B1); PG8_BAR; PG8_SCHED;
;     ...
;             PG8_LDB(B0, 1, 0); PG8_LDB(B1, 1, 1); PG8_SCHED; PG8_LDA(At, 1, 0); PG8_STAGEA(PG8_SA(0, 1), a2 + hstepA, voffA);
;             PG8_WAIT_V(8); PG8_WAIT_L(0); PG8_BAR; PG8_MMA(0, 0, At, B0); PG8_MMA(0, 1, At, B1); PG8_BAR; PG8_SCHED;
;             PG8_LDA(At, 1, 1); PG8_STAGEB(PG8_SB(1, 0), b3, voffB); PG8_STAGEB(PG8_SB(1, 1), b3 + hstepB, voffB); PG8_STAGEA(PG8_SA(1, 0), a3, voffA);
;             PG8_WAIT_V(8); PG8_WAIT_L(0); PG8_BAR; PG8_MMA(1, 0, At, B0); PG8_MMA(1, 1, At, B1); PG8_BAR; PG8_SCHED;
	v_mfma_f32_16x16x32_bf16 v[126:129], v[130:133], v[178:181], v[126:129]
	v_mfma_f32_16x16x32_bf16 v[122:125], v[148:151], v[178:181], v[122:125]
	v_mfma_f32_16x16x32_bf16 v[110:113], v[130:133], v[186:189], v[110:113]
	v_mfma_f32_16x16x32_bf16 v[106:109], v[148:151], v[186:189], v[106:109]
	v_mfma_f32_16x16x32_bf16 v[94:97], v[130:133], v[194:197], v[94:97]
	v_mfma_f32_16x16x32_bf16 v[90:93], v[148:151], v[194:197], v[90:93]
	v_mfma_f32_16x16x32_bf16 v[78:81], v[130:133], v[202:205], v[78:81]
	v_mfma_f32_16x16x32_bf16 v[74:77], v[148:151], v[202:205], v[74:77]
	v_mfma_f32_16x16x32_bf16 v[126:129], v[134:137], v[182:185], v[126:129]
	v_mfma_f32_16x16x32_bf16 v[122:125], v[152:155], v[182:185], v[122:125]
	v_mfma_f32_16x16x32_bf16 v[110:113], v[134:137], v[190:193], v[110:113]
	v_mfma_f32_16x16x32_bf16 v[106:109], v[152:155], v[190:193], v[106:109]
	v_mfma_f32_16x16x32_bf16 v[94:97], v[134:137], v[198:201], v[94:97]
	v_mfma_f32_16x16x32_bf16 v[90:93], v[152:155], v[198:201], v[90:93]
	v_mfma_f32_16x16x32_bf16 v[78:81], v[134:137], v[206:209], v[78:81]
	v_mfma_f32_16x16x32_bf16 v[74:77], v[152:155], v[206:209], v[74:77]
	v_mfma_f32_16x16x32_bf16 v[118:121], v[162:165], v[178:181], v[118:121]
	v_mfma_f32_16x16x32_bf16 v[114:117], v[170:173], v[178:181], v[114:117]
	v_mfma_f32_16x16x32_bf16 v[102:105], v[162:165], v[186:189], v[102:105]
	v_mfma_f32_16x16x32_bf16 v[98:101], v[170:173], v[186:189], v[98:101]
	v_mfma_f32_16x16x32_bf16 v[86:89], v[162:165], v[194:197], v[86:89]
	v_mfma_f32_16x16x32_bf16 v[82:85], v[170:173], v[194:197], v[82:85]
	v_mfma_f32_16x16x32_bf16 v[70:73], v[162:165], v[202:205], v[70:73]
	v_mfma_f32_16x16x32_bf16 v[66:69], v[170:173], v[202:205], v[66:69]
	v_mfma_f32_16x16x32_bf16 v[118:121], v[166:169], v[182:185], v[118:121]
	v_mfma_f32_16x16x32_bf16 v[114:117], v[174:177], v[182:185], v[114:117]
	v_mfma_f32_16x16x32_bf16 v[102:105], v[166:169], v[190:193], v[102:105]
	v_mfma_f32_16x16x32_bf16 v[98:101], v[174:177], v[190:193], v[98:101]
	v_mfma_f32_16x16x32_bf16 v[86:89], v[166:169], v[198:201], v[86:89]
	v_mfma_f32_16x16x32_bf16 v[82:85], v[174:177], v[198:201], v[82:85]
	v_mfma_f32_16x16x32_bf16 v[70:73], v[166:169], v[206:209], v[70:73]
	v_mfma_f32_16x16x32_bf16 v[66:69], v[174:177], v[206:209], v[66:69]
	s_barrier
	s_add_i32 s83, s38, 0x10000
	s_mov_b32 m0, s83
	ds_read_b128 v[178:181], v161 offset:16384
	ds_read_b128 v[182:185], v161 offset:17408
	ds_read_b128 v[186:189], v161 offset:18432
	ds_read_b128 v[190:193], v161 offset:19456
	global_load_lds_dwordx4 v16, s[16:17]
	s_add_i32 m0, s83, 0x2000
	s_add_u32 s90, s16, 0x4000
	s_addc_u32 s91, s17, 0
	s_add_i32 s83, s94, s38
	global_load_lds_dwordx4 v138, s[16:17]
	s_mov_b32 m0, s83
	ds_read_b128 v[206:209], v161 offset:23552
	global_load_lds_dwordx4 v16, s[90:91]
	s_add_i32 m0, s83, 0x2000
	ds_read_b128 v[202:205], v161 offset:22528
	global_load_lds_dwordx4 v138, s[90:91]
	s_mov_b32 m0, s39
	ds_read_b128 v[198:201], v161 offset:21504
	global_load_lds_dwordx4 v142, s[36:37]
	s_mov_b32 m0, s40
	ds_read_b128 v[194:197], v161 offset:20480
	global_load_lds_dwordx4 v140, s[36:37]
	s_waitcnt vmcnt(8) lgkmcnt(0)
	s_nop 0
	s_barrier
	v_mfma_f32_16x16x32_bf16 v[62:65], v[130:133], v[178:181], v[62:65]
	v_mfma_f32_16x16x32_bf16 v[58:61], v[148:151], v[178:181], v[58:61]
	v_mfma_f32_16x16x32_bf16 v[46:49], v[130:133], v[186:189], v[46:49]
	v_mfma_f32_16x16x32_bf16 v[42:45], v[148:151], v[186:189], v[42:45]
	v_mfma_f32_16x16x32_bf16 v[30:33], v[130:133], v[194:197], v[30:33]
	v_mfma_f32_16x16x32_bf16 v[26:29], v[148:151], v[194:197], v[26:29]
	v_mfma_f32_16x16x32_bf16 v[12:15], v[130:133], v[202:205], v[12:15]
	v_mfma_f32_16x16x32_bf16 v[8:11], v[148:151], v[202:205], v[8:11]
	v_mfma_f32_16x16x32_bf16 v[62:65], v[134:137], v[182:185], v[62:65]
	v_mfma_f32_16x16x32_bf16 v[58:61], v[152:155], v[182:185], v[58:61]
	v_mfma_f32_16x16x32_bf16 v[46:49], v[134:137], v[190:193], v[46:49]
	v_mfma_f32_16x16x32_bf16 v[42:45], v[152:155], v[190:193], v[42:45]
	v_mfma_f32_16x16x32_bf16 v[30:33], v[134:137], v[198:201], v[30:33]
	v_mfma_f32_16x16x32_bf16 v[26:29], v[152:155], v[198:201], v[26:29]
	v_mfma_f32_16x16x32_bf16 v[12:15], v[134:137], v[206:209], v[12:15]
	v_mfma_f32_16x16x32_bf16 v[8:11], v[152:155], v[206:209], v[8:11]
	v_mfma_f32_16x16x32_bf16 v[54:57], v[162:165], v[178:181], v[54:57]
	v_mfma_f32_16x16x32_bf16 v[50:53], v[170:173], v[178:181], v[50:53]
	v_mfma_f32_16x16x32_bf16 v[38:41], v[162:165], v[186:189], v[38:41]
	v_mfma_f32_16x16x32_bf16 v[34:37], v[170:173], v[186:189], v[34:37]
	v_mfma_f32_16x16x32_bf16 v[22:25], v[162:165], v[194:197], v[22:25]
	v_mfma_f32_16x16x32_bf16 v[18:21], v[170:173], v[194:197], v[18:21]
	v_mfma_f32_16x16x32_bf16 v[4:7], v[162:165], v[202:205], v[4:7]
	v_mfma_f32_16x16x32_bf16 v[0:3], v[170:173], v[202:205], v[0:3]
	v_mfma_f32_16x16x32_bf16 v[54:57], v[166:169], v[182:185], v[54:57]
	v_mfma_f32_16x16x32_bf16 v[50:53], v[174:177], v[182:185], v[50:53]
	v_mfma_f32_16x16x32_bf16 v[38:41], v[166:169], v[190:193], v[38:41]
	v_mfma_f32_16x16x32_bf16 v[34:37], v[174:177], v[190:193], v[34:37]
	v_mfma_f32_16x16x32_bf16 v[22:25], v[166:169], v[198:201], v[22:25]
	v_mfma_f32_16x16x32_bf16 v[18:21], v[174:177], v[198:201], v[18:21]
	v_mfma_f32_16x16x32_bf16 v[4:7], v[166:169], v[206:209], v[4:7]
	v_mfma_f32_16x16x32_bf16 v[0:3], v[174:177], v[206:209], v[0:3]
	s_barrier
; #define PG8_STAGEA(bufoff, gbase, voff) PG8_STAGE_X(bufoff, gbase, voff, AUXA)
; #define PG8_STAGEB(bufoff, gbase, voff) PG8_STAGE_X(bufoff, gbase, voff, AUXB)
; #define PG8_LDA(dst, b, h) do { _Pragma("unroll") for (int m = 0; m < 4; ++m) _Pragma("unroll") for (int k = 0; k < 2; ++k) dst[m][k] = *(const PG8_LAS bf16x8*)(lds + PG8_SA(b, h) + aoff + m * 2048 + k * 1024); } while (0)
; #define PG8_LDB(dst, b, h) do { _Pragma("unroll") for (int n = 0; n < 2; ++n) _Pragma("unroll") for (int k = 0; k < 2; ++k) dst[n][k] = *(const PG8_LAS bf16x8*)(lds + PG8_SB(b, h) + boff + n * 2048 + k * 1024); } while (0)
; #define PG8_MMA(ai, bj, At, Bt) do { if (GEMM_PRIO_MODE == 0) __builtin_amdgcn_s_setprio(1); PG8_MMA_LOOPS \
;         acc[ai][bj][m][n] = __builtin_amdgcn_mfma_f32_16x16x32_bf16(Bt[n][k], At[m][k], acc[ai][bj][m][n], 0, 0, 0); if (GEMM_PRIO_MODE == 0) __builtin_amdgcn_s_setprio(0); } while (0)
; #define PG8_WAIT_V(n) asm volatile("s_waitcnt vmcnt(" #n ")" ::: "memory")
;     ...
;             PG8_LDB(B0, 0, 0); PG8_LDB(B1, 0, 1); PG8_SCHED; PG8_LDA(At, 0, 0); PG8_STAGEA(PG8_SA(1, 1), a1 + hstepA, voffA);
;     ...
;             const int relax = __builtin_amdgcn_readfirstlane((t == 0 && ui > 0) ? 1 : 0);
;             PG8_WAIT_VR(8, 24, relax); PG8_WAIT_L(0); PG8_BAR; PG8_MMA(0, 0, At, B0); PG8_MMA(0, 1, At, B1); PG8_BAR; PG8_SCHED;
;     ...
;             PG8_WAIT_V(8); PG8_WAIT_L(0); PG8_BAR; PG8_MMA(0, 0, At, B0); PG8_MMA(0, 1, At, B1); PG8_BAR; PG8_SCHED;
;     ...
;             PG8_LDA(At, 0, 1); PG8_STAGEB(PG8_SB(0, 0), b2, voffB); PG8_STAGEB(PG8_SB(0, 1), b2 + hstepB, voffB); PG8_STAGEA(PG8_SA(0, 0), a2, voffA);
;     ...
;             PG8_WAIT_VR(8, 24, relax); PG8_WAIT_L(0); PG8_BAR; PG8_MMA(1, 0, At, B0); PG8_MMA(1, 1, At, B1); PG8_BAR; PG8_SCHED;
;     ...
;             PG8_WAIT_V(8); PG8_WAIT_L(0); PG8_BAR; PG8_MMA(1, 0, At, B0); PG8_MMA(1, 1, At, B1); PG8_BAR; PG8_SCHED;
;     ...
;             PG8_LDB(B0, 1, 0); PG8_LDB(B1, 1, 1); PG8_SCHED; PG8_LDA(At, 1, 0); PG8_STAGEA(PG8_SA(0, 1), a2 + hstepA, voffA);
;             PG8_WAIT_V(8); PG8_WAIT_L(0); PG8_BAR; PG8_MMA(0, 0, At, B0); PG8_MMA(0, 1, At, B1); PG8_BAR; PG8_SCHED;
;             PG8_LDA(At, 1, 1); PG8_STAGEB(PG8_SB(1, 0), b3, voffB); PG8_STAGEB(PG8_SB(1, 1), b3 + hstepB, voffB); PG8_STAGEA(PG8_SA(1, 0), a3, voffA);
;             PG8_WAIT_V(8); PG8_WAIT_L(0); PG8_BAR; PG8_MMA(1, 0, At, B0); PG8_MMA(1, 1, At, B1); PG8_BAR; PG8_SCHED;
	ds_read_b128 v[130:133], v212 offset:32768
	ds_read_b128 v[134:137], v212 offset:33792
	ds_read_b128 v[148:151], v212 offset:34816
	ds_read_b128 v[152:155], v212 offset:35840
	ds_read_b128 v[162:165], v212 offset:49152
	ds_read_b128 v[166:169], v212 offset:50176
	ds_read_b128 v[170:173], v212 offset:51200
	ds_read_b128 v[174:177], v212 offset:52224
	s_add_u32 s36, s36, 0x4000
	s_addc_u32 s37, s37, 0
	s_mov_b32 m0, s41
	ds_read_b128 v[178:181], v161 offset:32768
	ds_read_b128 v[182:185], v161 offset:33792
	ds_read_b128 v[186:189], v161 offset:34816
	ds_read_b128 v[190:193], v161 offset:35840
	ds_read_b128 v[194:197], v161 offset:36864
	ds_read_b128 v[198:201], v161 offset:37888
	ds_read_b128 v[202:205], v161 offset:38912
	global_load_lds_dwordx4 v142, s[36:37]
	s_mov_b32 m0, s42
	ds_read_b128 v[206:209], v161 offset:39936
	global_load_lds_dwordx4 v140, s[36:37]
	s_waitcnt vmcnt(8) lgkmcnt(0)
	s_barrier
	v_mfma_f32_16x16x32_bf16 v[126:129], v[130:133], v[178:181], v[126:129]
	v_mfma_f32_16x16x32_bf16 v[122:125], v[148:151], v[178:181], v[122:125]
	v_mfma_f32_16x16x32_bf16 v[110:113], v[130:133], v[186:189], v[110:113]
	v_mfma_f32_16x16x32_bf16 v[106:109], v[148:151], v[186:189], v[106:109]
	v_mfma_f32_16x16x32_bf16 v[94:97], v[130:133], v[194:197], v[94:97]
	v_mfma_f32_16x16x32_bf16 v[90:93], v[148:151], v[194:197], v[90:93]
	v_mfma_f32_16x16x32_bf16 v[78:81], v[130:133], v[202:205], v[78:81]
	v_mfma_f32_16x16x32_bf16 v[74:77], v[148:151], v[202:205], v[74:77]
	v_mfma_f32_16x16x32_bf16 v[126:129], v[134:137], v[182:185], v[126:129]
	v_mfma_f32_16x16x32_bf16 v[122:125], v[152:155], v[182:185], v[122:125]
	v_mfma_f32_16x16x32_bf16 v[110:113], v[134:137], v[190:193], v[110:113]
	v_mfma_f32_16x16x32_bf16 v[106:109], v[152:155], v[190:193], v[106:109]
	v_mfma_f32_16x16x32_bf16 v[94:97], v[134:137], v[198:201], v[94:97]
	v_mfma_f32_16x16x32_bf16 v[90:93], v[152:155], v[198:201], v[90:93]
	v_mfma_f32_16x16x32_bf16 v[78:81], v[134:137], v[206:209], v[78:81]
	v_mfma_f32_16x16x32_bf16 v[74:77], v[152:155], v[206:209], v[74:77]
	v_mfma_f32_16x16x32_bf16 v[118:121], v[162:165], v[178:181], v[118:121]
	v_mfma_f32_16x16x32_bf16 v[114:117], v[170:173], v[178:181], v[114:117]
	v_mfma_f32_16x16x32_bf16 v[102:105], v[162:165], v[186:189], v[102:105]
	v_mfma_f32_16x16x32_bf16 v[98:101], v[170:173], v[186:189], v[98:101]
	v_mfma_f32_16x16x32_bf16 v[86:89], v[162:165], v[194:197], v[86:89]
	v_mfma_f32_16x16x32_bf16 v[82:85], v[170:173], v[194:197], v[82:85]
	v_mfma_f32_16x16x32_bf16 v[70:73], v[162:165], v[202:205], v[70:73]
	v_mfma_f32_16x16x32_bf16 v[66:69], v[170:173], v[202:205], v[66:69]
	v_mfma_f32_16x16x32_bf16 v[118:121], v[166:169], v[182:185], v[118:121]
	v_mfma_f32_16x16x32_bf16 v[114:117], v[174:177], v[182:185], v[114:117]
	v_mfma_f32_16x16x32_bf16 v[102:105], v[166:169], v[190:193], v[102:105]
	v_mfma_f32_16x16x32_bf16 v[98:101], v[174:177], v[190:193], v[98:101]
	v_mfma_f32_16x16x32_bf16 v[86:89], v[166:169], v[198:201], v[86:89]
	v_mfma_f32_16x16x32_bf16 v[82:85], v[174:177], v[198:201], v[82:85]
	v_mfma_f32_16x16x32_bf16 v[70:73], v[166:169], v[206:209], v[70:73]
	v_mfma_f32_16x16x32_bf16 v[66:69], v[174:177], v[206:209], v[66:69]
	s_barrier
	s_add_u32 s36, s16, 0x8000
	s_addc_u32 s37, s17, 0
	s_add_i32 s83, s38, 0x18000
	s_mov_b32 m0, s83
	ds_read_b128 v[178:181], v161 offset:49152
	ds_read_b128 v[182:185], v161 offset:50176
	ds_read_b128 v[186:189], v161 offset:51200
	ds_read_b128 v[190:193], v161 offset:52224
	global_load_lds_dwordx4 v16, s[36:37]
	s_add_i32 m0, s83, 0x2000
	s_add_u32 s16, s16, 0xc000
	s_addc_u32 s17, s17, 0
	global_load_lds_dwordx4 v138, s[36:37]
	s_add_i32 s36, s38, 0x1c000
	s_mov_b32 m0, s36
	ds_read_b128 v[206:209], v161 offset:56320
	global_load_lds_dwordx4 v16, s[16:17]
	s_add_i32 m0, s36, 0x2000
	ds_read_b128 v[202:205], v161 offset:55296
	global_load_lds_dwordx4 v138, s[16:17]
	s_mov_b32 m0, s50
	ds_read_b128 v[198:201], v161 offset:54272
	global_load_lds_dwordx4 v142, s[26:27]
	s_mov_b32 m0, s51
	ds_read_b128 v[194:197], v161 offset:53248
	global_load_lds_dwordx4 v140, s[26:27]
	s_waitcnt vmcnt(8) lgkmcnt(0)
	s_nop 0
	s_nop 0
	s_nop 0
	s_barrier
	v_mfma_f32_16x16x32_bf16 v[62:65], v[130:133], v[178:181], v[62:65]
	v_mfma_f32_16x16x32_bf16 v[58:61], v[148:151], v[178:181], v[58:61]
	v_mfma_f32_16x16x32_bf16 v[46:49], v[130:133], v[186:189], v[46:49]
	v_mfma_f32_16x16x32_bf16 v[42:45], v[148:151], v[186:189], v[42:45]
	v_mfma_f32_16x16x32_bf16 v[30:33], v[130:133], v[194:197], v[30:33]
	v_mfma_f32_16x16x32_bf16 v[26:29], v[148:151], v[194:197], v[26:29]
	v_mfma_f32_16x16x32_bf16 v[12:15], v[130:133], v[202:205], v[12:15]
	v_mfma_f32_16x16x32_bf16 v[8:11], v[148:151], v[202:205], v[8:11]
	v_mfma_f32_16x16x32_bf16 v[62:65], v[134:137], v[182:185], v[62:65]
	v_mfma_f32_16x16x32_bf16 v[58:61], v[152:155], v[182:185], v[58:61]
	v_mfma_f32_16x16x32_bf16 v[46:49], v[134:137], v[190:193], v[46:49]
	v_mfma_f32_16x16x32_bf16 v[42:45], v[152:155], v[190:193], v[42:45]
	v_mfma_f32_16x16x32_bf16 v[30:33], v[134:137], v[198:201], v[30:33]
	v_mfma_f32_16x16x32_bf16 v[26:29], v[152:155], v[198:201], v[26:29]
	v_mfma_f32_16x16x32_bf16 v[12:15], v[134:137], v[206:209], v[12:15]
	v_mfma_f32_16x16x32_bf16 v[8:11], v[152:155], v[206:209], v[8:11]
	v_mfma_f32_16x16x32_bf16 v[54:57], v[162:165], v[178:181], v[54:57]
	v_mfma_f32_16x16x32_bf16 v[50:53], v[170:173], v[178:181], v[50:53]
	v_mfma_f32_16x16x32_bf16 v[38:41], v[162:165], v[186:189], v[38:41]
	v_mfma_f32_16x16x32_bf16 v[34:37], v[170:173], v[186:189], v[34:37]
	v_mfma_f32_16x16x32_bf16 v[22:25], v[162:165], v[194:197], v[22:25]
	v_mfma_f32_16x16x32_bf16 v[18:21], v[170:173], v[194:197], v[18:21]
	v_mfma_f32_16x16x32_bf16 v[4:7], v[162:165], v[202:205], v[4:7]
	v_mfma_f32_16x16x32_bf16 v[0:3], v[170:173], v[202:205], v[0:3]
	v_mfma_f32_16x16x32_bf16 v[54:57], v[166:169], v[182:185], v[54:57]
	v_mfma_f32_16x16x32_bf16 v[50:53], v[174:177], v[182:185], v[50:53]
	v_mfma_f32_16x16x32_bf16 v[38:41], v[166:169], v[190:193], v[38:41]
	v_mfma_f32_16x16x32_bf16 v[34:37], v[174:177], v[190:193], v[34:37]
	v_mfma_f32_16x16x32_bf16 v[22:25], v[166:169], v[198:201], v[22:25]
	v_mfma_f32_16x16x32_bf16 v[18:21], v[174:177], v[198:201], v[18:21]
	v_mfma_f32_16x16x32_bf16 v[4:7], v[166:169], v[206:209], v[4:7]
	v_mfma_f32_16x16x32_bf16 v[0:3], v[174:177], v[206:209], v[0:3]
	s_barrier
	s_add_i32 s82, s82, 2
	s_add_u32 s24, s24, 0x10000
	s_addc_u32 s25, s25, 0
	s_add_u32 s0, s0, 0x10000
	s_addc_u32 s1, s1, 0
	s_cmpk_gt_u32 s82, 0xfd
	s_cbranch_scc0 .LBB0_848
	s_and_b64 vcc, exec, s[8:9]
	s_cbranch_vccz .LBB0_851
	s_barrier
